# ctx_combine norm-apply half: the 12 loop-invariant gain / shift / scale vector loads issued before the row reduction instead of three per stage behind a full wait
# speedup vs baseline: 1.0085x; 1.0028x over previous
; DEVI void ctx_combine_phase(const Params& p, int l, int gi, float coef, int ln, int lwhich) {
;     ...
;   for (int rc = gw; rc < TC; rc += NW) {
;     f32x4* x4 = (f32x4*)(X + (size_t)(TL + rc) * D) + lane;
;     f32x4 v[4]; float ss = 0.f;
; #pragma unroll
;     for (int j = 0; j < 4; ++j) {
;       f32x4 sum = {0.f, 0.f, 0.f, 0.f};
; #pragma unroll
;       for (int sl = 0; sl < 7; ++sl) {
;         const uint2 w = *((const uint2*)(PS + ((size_t)sl * TC + rc) * D) + lane + 64 * j);
;         sum[0] += __uint_as_float(w.x << 16); sum[1] += __uint_as_float(w.x & 0xffff0000u); sum[2] += __uint_as_float(w.y << 16); sum[3] += __uint_as_float(w.y & 0xffff0000u);
;       }
;       const f32x4 xo = x4[64 * j], gv = gate4[64 * j];
; #pragma unroll
;       for (int q = 0; q < 4; ++q) v[j][q] = xo[q] + coef * gv[q] * sum[q];
;       x4[64 * j] = v[j];
;       ss += (v[j][0] * v[j][0] + v[j][1] * v[j][1]) + (v[j][2] * v[j][2] + v[j][3] * v[j][3]);
.LBB0_1040:
	v_add_co_u32_e32 v12, vcc, 0xfe800000, v50
	v_add_u32_e32 v16, 0x8000, v24
	s_nop 0
	v_addc_co_u32_e32 v13, vcc, -1, v51, vcc
	v_add_co_u32_e32 v14, vcc, 0xfec00000, v50
	v_ashrrev_i32_e32 v17, 31, v16
	s_nop 0
	v_addc_co_u32_e32 v15, vcc, -1, v51, vcc
	v_add_co_u32_e32 v22, vcc, 0xff000000, v50
	v_lshlrev_b64 v[0:1], 12, v[16:17]
	s_nop 0
	v_addc_co_u32_e32 v23, vcc, -1, v51, vcc
	v_add_co_u32_e32 v52, vcc, 0xff400000, v50
	v_lshl_add_u64 v[18:19], v[28:29], 0, v[0:1]
	s_nop 0
	v_addc_co_u32_e32 v53, vcc, -1, v51, vcc
	v_add_co_u32_e32 v54, vcc, 0xff800000, v50
	global_load_dwordx2 v[10:11], v[52:53], off offset:-1540
	s_nop 0
	v_addc_co_u32_e32 v55, vcc, -1, v51, vcc
	global_load_dwordx2 v[56:57], v[54:55], off offset:-1540
	global_load_dwordx2 v[0:1], v[12:13], off offset:-1540
	global_load_dwordx2 v[2:3], v[14:15], off offset:-1540
	global_load_dwordx2 v[6:7], v[22:23], off offset:-1540
	v_add_co_u32_e32 v98, vcc, 0xffc00000, v50
	s_nop 1
	v_addc_co_u32_e32 v99, vcc, -1, v51, vcc
	global_load_dwordx2 v[100:101], v[98:99], off offset:-1540
	global_load_dwordx2 v[102:103], v[50:51], off offset:-1540
	global_load_dwordx4 v[104:107], v[18:19], off
	global_load_dwordx4 v[108:111], v[26:27], off
	global_load_dwordx2 v[112:113], v[12:13], off offset:-1028
	global_load_dwordx2 v[114:115], v[14:15], off offset:-1028
	global_load_dwordx2 v[116:117], v[22:23], off offset:-1028
	global_load_dwordx2 v[118:119], v[52:53], off offset:-1028
	global_load_dwordx2 v[120:121], v[54:55], off offset:-1028
	global_load_dwordx2 v[122:123], v[98:99], off offset:-1028
	global_load_dwordx2 v[124:125], v[50:51], off offset:-1028
	global_load_dwordx4 v[126:129], v[18:19], off offset:1024
	global_load_dwordx4 v[130:133], v[26:27], off offset:1024
	global_load_dwordx2 v[134:135], v[12:13], off offset:-516
	global_load_dwordx2 v[136:137], v[14:15], off offset:-516
	global_load_dwordx2 v[138:139], v[22:23], off offset:-516
	global_load_dwordx2 v[140:141], v[52:53], off offset:-516
	global_load_dwordx2 v[142:143], v[54:55], off offset:-516
	global_load_dwordx2 v[144:145], v[98:99], off offset:-516
	global_load_dwordx2 v[146:147], v[50:51], off offset:-516
	global_load_dwordx4 v[152:155], v[18:19], off offset:2048
	global_load_dwordx4 v[156:159], v[26:27], off offset:2048
	global_load_dwordx2 v[160:161], v[12:13], off offset:-4
	global_load_dwordx2 v[162:163], v[14:15], off offset:-4
	global_load_dwordx2 v[164:165], v[22:23], off offset:-4
	global_load_dwordx2 v[166:167], v[52:53], off offset:-4
	global_load_dwordx2 v[168:169], v[54:55], off offset:-4
	global_load_dwordx2 v[170:171], v[98:99], off offset:-4
	global_load_dwordx2 v[172:173], v[50:51], off offset:-4
	global_load_dwordx4 v[176:179], v[18:19], off offset:3072
	global_load_dwordx4 v[180:183], v[26:27], off offset:3072
	v_lshlrev_b64 v[16:17], 11, v[16:17]
	v_add_u32_e32 v24, s2, v24
	s_waitcnt vmcnt(4)
	v_lshlrev_b32_e32 v60, 16, v10
	v_and_b32_e32 v61, 0xffff0000, v10
	v_lshlrev_b32_e32 v10, 16, v11
	s_waitcnt vmcnt(3)
	v_lshlrev_b32_e32 v70, 16, v56
	v_and_b32_e32 v71, 0xffff0000, v56
	v_add_co_u32_e32 v56, vcc, 0xffc00000, v50
	v_lshlrev_b32_e32 v58, 16, v57
	v_and_b32_e32 v59, 0xffff0000, v57
	v_addc_co_u32_e32 v57, vcc, -1, v51, vcc
	v_and_b32_e32 v11, 0xffff0000, v11
	s_waitcnt vmcnt(0)
	v_mov_b32_e32 v62, v100
	v_mov_b32_e32 v63, v101
	v_lshlrev_b32_e32 v72, 16, v62
	v_and_b32_e32 v73, 0xffff0000, v62
	v_lshlrev_b32_e32 v74, 16, v63
	v_and_b32_e32 v75, 0xffff0000, v63
	v_lshlrev_b32_e32 v4, 16, v0
	v_and_b32_e32 v5, 0xffff0000, v0
	v_lshlrev_b32_e32 v0, 16, v1
	v_and_b32_e32 v1, 0xffff0000, v1
	v_lshlrev_b32_e32 v8, 16, v2
	v_and_b32_e32 v9, 0xffff0000, v2
	v_lshlrev_b32_e32 v2, 16, v3
	v_and_b32_e32 v3, 0xffff0000, v3
	v_pk_add_f32 v[4:5], v[4:5], 0 op_sel_hi:[1,0]
	v_pk_add_f32 v[0:1], v[0:1], 0 op_sel_hi:[1,0]
	v_lshlrev_b32_e32 v20, 16, v6
	v_and_b32_e32 v21, 0xffff0000, v6
	v_lshlrev_b32_e32 v6, 16, v7
	v_and_b32_e32 v7, 0xffff0000, v7
	v_pk_add_f32 v[4:5], v[4:5], v[8:9]
	v_pk_add_f32 v[0:1], v[0:1], v[2:3]
	v_pk_add_f32 v[4:5], v[4:5], v[20:21]
	v_pk_add_f32 v[0:1], v[0:1], v[6:7]
	v_pk_add_f32 v[4:5], v[4:5], v[60:61]
	v_pk_add_f32 v[0:1], v[0:1], v[10:11]
	v_pk_add_f32 v[4:5], v[4:5], v[70:71]
	v_pk_add_f32 v[0:1], v[0:1], v[58:59]
	v_pk_add_f32 v[4:5], v[4:5], v[72:73]
	v_pk_add_f32 v[0:1], v[0:1], v[74:75]
	s_waitcnt vmcnt(0)
	v_mov_b32_e32 v62, v102
	v_mov_b32_e32 v63, v103
	v_lshlrev_b32_e32 v76, 16, v62
	v_and_b32_e32 v77, 0xffff0000, v62
	v_lshlrev_b32_e32 v78, 16, v63
	v_and_b32_e32 v79, 0xffff0000, v63
	v_pk_add_f32 v[4:5], v[4:5], v[76:77]
	v_pk_add_f32 v[0:1], v[0:1], v[78:79]
	s_waitcnt vmcnt(0)
	v_mov_b32_e32 v66, v108
	v_mov_b32_e32 v67, v109
	v_mov_b32_e32 v68, v110
	v_mov_b32_e32 v69, v111
	v_mov_b32_e32 v62, v104
	v_mov_b32_e32 v63, v105
	v_mov_b32_e32 v64, v106
	v_mov_b32_e32 v65, v107
	v_pk_mul_f32 v[8:9], v[66:67], 0.5 op_sel_hi:[1,0]
	v_pk_mul_f32 v[2:3], v[68:69], 0.5 op_sel_hi:[1,0]
	v_pk_fma_f32 v[8:9], v[4:5], v[8:9], v[62:63]
	v_pk_fma_f32 v[10:11], v[0:1], v[2:3], v[64:65]
	v_mov_b32_e32 v2, v9
	v_mov_b32_e32 v3, v11
	v_mov_b32_e32 v0, v8
	v_mov_b32_e32 v1, v10
	v_pk_mul_f32 v[2:3], v[2:3], v[2:3]
	global_store_dwordx4 v[18:19], v[8:11], off
	v_pk_fma_f32 v[0:1], v[0:1], v[0:1], v[2:3]
	s_nop 0
	v_pk_add_f32 v[20:21], v[0:1], v[0:1] op_sel:[0,1] op_sel_hi:[1,0]
	s_waitcnt vmcnt(0)
	v_mov_b32_e32 v0, v112
	v_mov_b32_e32 v1, v113
	v_lshlrev_b32_e32 v58, 16, v0
	v_and_b32_e32 v59, 0xffff0000, v0
	v_lshlrev_b32_e32 v4, 16, v1
	v_and_b32_e32 v5, 0xffff0000, v1
	v_pk_add_f32 v[58:59], v[58:59], 0 op_sel_hi:[1,0]
	v_pk_add_f32 v[4:5], v[4:5], 0 op_sel_hi:[1,0]
	s_waitcnt vmcnt(0)
; DEVI void ctx_combine_phase(const Params& p, int l, int gi, float coef, int ln, int lwhich) {
;     ...
;     for (int j = 0; j < 4; ++j) {
;       f32x4 sum = {0.f, 0.f, 0.f, 0.f};
; #pragma unroll
;       for (int sl = 0; sl < 7; ++sl) {
;         const uint2 w = *((const uint2*)(PS + ((size_t)sl * TC + rc) * D) + lane + 64 * j);
;         sum[0] += __uint_as_float(w.x << 16); sum[1] += __uint_as_float(w.x & 0xffff0000u); sum[2] += __uint_as_float(w.y << 16); sum[3] += __uint_as_float(w.y & 0xffff0000u);
;       }
;       const f32x4 xo = x4[64 * j], gv = gate4[64 * j];
; #pragma unroll
;       for (int q = 0; q < 4; ++q) v[j][q] = xo[q] + coef * gv[q] * sum[q];
;       x4[64 * j] = v[j];
;       ss += (v[j][0] * v[j][0] + v[j][1] * v[j][1]) + (v[j][2] * v[j][2] + v[j][3] * v[j][3]);
	v_mov_b32_e32 v0, v114
	v_mov_b32_e32 v1, v115
	v_lshlrev_b32_e32 v62, 16, v0
	v_and_b32_e32 v63, 0xffff0000, v0
	v_lshlrev_b32_e32 v6, 16, v1
	v_and_b32_e32 v7, 0xffff0000, v1
	v_pk_add_f32 v[58:59], v[58:59], v[62:63]
	v_pk_add_f32 v[4:5], v[4:5], v[6:7]
	s_waitcnt vmcnt(0)
	v_mov_b32_e32 v0, v116
	v_mov_b32_e32 v1, v117
	v_lshlrev_b32_e32 v66, 16, v0
	v_and_b32_e32 v67, 0xffff0000, v0
	v_lshlrev_b32_e32 v60, 16, v1
	v_and_b32_e32 v61, 0xffff0000, v1
	v_pk_add_f32 v[58:59], v[58:59], v[66:67]
	v_pk_add_f32 v[4:5], v[4:5], v[60:61]
	s_waitcnt vmcnt(0)
	v_mov_b32_e32 v0, v118
	v_mov_b32_e32 v1, v119
	v_lshlrev_b32_e32 v70, 16, v0
	v_and_b32_e32 v71, 0xffff0000, v0
	v_lshlrev_b32_e32 v64, 16, v1
	v_and_b32_e32 v65, 0xffff0000, v1
	v_pk_add_f32 v[58:59], v[58:59], v[70:71]
	v_pk_add_f32 v[4:5], v[4:5], v[64:65]
	s_waitcnt vmcnt(0)
	v_mov_b32_e32 v0, v120
	v_mov_b32_e32 v1, v121
	v_lshlrev_b32_e32 v74, 16, v0
	v_and_b32_e32 v75, 0xffff0000, v0
	v_lshlrev_b32_e32 v68, 16, v1
	v_and_b32_e32 v69, 0xffff0000, v1
	v_pk_add_f32 v[58:59], v[58:59], v[74:75]
	v_pk_add_f32 v[4:5], v[4:5], v[68:69]
	s_waitcnt vmcnt(0)
	v_mov_b32_e32 v0, v122
	v_mov_b32_e32 v1, v123
	v_lshlrev_b32_e32 v78, 16, v0
	v_and_b32_e32 v79, 0xffff0000, v0
	v_lshlrev_b32_e32 v72, 16, v1
	v_and_b32_e32 v73, 0xffff0000, v1
	v_pk_add_f32 v[58:59], v[58:59], v[78:79]
	v_pk_add_f32 v[4:5], v[4:5], v[72:73]
	s_waitcnt vmcnt(0)
	v_mov_b32_e32 v0, v124
	v_mov_b32_e32 v1, v125
	v_lshlrev_b32_e32 v80, 16, v0
	v_and_b32_e32 v81, 0xffff0000, v0
	v_lshlrev_b32_e32 v76, 16, v1
	v_and_b32_e32 v77, 0xffff0000, v1
	v_pk_add_f32 v[58:59], v[58:59], v[80:81]
	v_pk_add_f32 v[4:5], v[4:5], v[76:77]
	s_waitcnt vmcnt(0)
	v_mov_b32_e32 v82, v130
	v_mov_b32_e32 v83, v131
	v_mov_b32_e32 v84, v132
	v_mov_b32_e32 v85, v133
	v_mov_b32_e32 v0, v126
	v_mov_b32_e32 v1, v127
	v_mov_b32_e32 v2, v128
	v_mov_b32_e32 v3, v129
	v_pk_mul_f32 v[62:63], v[82:83], 0.5 op_sel_hi:[1,0]
	v_pk_mul_f32 v[6:7], v[84:85], 0.5 op_sel_hi:[1,0]
	v_pk_fma_f32 v[0:1], v[58:59], v[62:63], v[0:1]
	v_pk_fma_f32 v[2:3], v[4:5], v[6:7], v[2:3]
	v_mov_b32_e32 v6, v1
	v_mov_b32_e32 v7, v3
	v_mov_b32_e32 v4, v0
	v_mov_b32_e32 v5, v2
	v_pk_mul_f32 v[6:7], v[6:7], v[6:7]
	global_store_dwordx4 v[18:19], v[0:3], off offset:1024
	v_pk_fma_f32 v[4:5], v[4:5], v[4:5], v[6:7]
	s_nop 0
	v_pk_add_f32 v[58:59], v[4:5], v[4:5] op_sel:[0,1] op_sel_hi:[1,0]
	s_waitcnt vmcnt(0)
	v_mov_b32_e32 v4, v134
	v_mov_b32_e32 v5, v135
	v_lshlrev_b32_e32 v64, 16, v4
	v_and_b32_e32 v65, 0xffff0000, v4
	v_lshlrev_b32_e32 v60, 16, v5
	v_and_b32_e32 v61, 0xffff0000, v5
	v_pk_add_f32 v[64:65], v[64:65], 0 op_sel_hi:[1,0]
	v_pk_add_f32 v[60:61], v[60:61], 0 op_sel_hi:[1,0]
	s_waitcnt vmcnt(0)
	v_mov_b32_e32 v4, v136
	v_mov_b32_e32 v5, v137
	v_lshlrev_b32_e32 v68, 16, v4
	v_and_b32_e32 v69, 0xffff0000, v4
	v_lshlrev_b32_e32 v62, 16, v5
	v_and_b32_e32 v63, 0xffff0000, v5
	v_pk_add_f32 v[64:65], v[64:65], v[68:69]
	v_pk_add_f32 v[60:61], v[60:61], v[62:63]
	s_waitcnt vmcnt(0)
	v_mov_b32_e32 v4, v138
	v_mov_b32_e32 v5, v139
	v_lshlrev_b32_e32 v72, 16, v4
	v_and_b32_e32 v73, 0xffff0000, v4
	v_lshlrev_b32_e32 v66, 16, v5
	v_and_b32_e32 v67, 0xffff0000, v5
	v_pk_add_f32 v[64:65], v[64:65], v[72:73]
	v_pk_add_f32 v[60:61], v[60:61], v[66:67]
	s_waitcnt vmcnt(0)
	v_mov_b32_e32 v4, v140
	v_mov_b32_e32 v5, v141
	v_lshlrev_b32_e32 v76, 16, v4
	v_and_b32_e32 v77, 0xffff0000, v4
	v_lshlrev_b32_e32 v70, 16, v5
	v_and_b32_e32 v71, 0xffff0000, v5
	v_pk_add_f32 v[64:65], v[64:65], v[76:77]
	v_pk_add_f32 v[60:61], v[60:61], v[70:71]
	s_waitcnt vmcnt(0)
	v_mov_b32_e32 v4, v142
	v_mov_b32_e32 v5, v143
	v_lshlrev_b32_e32 v80, 16, v4
	v_and_b32_e32 v81, 0xffff0000, v4
	v_lshlrev_b32_e32 v74, 16, v5
	v_and_b32_e32 v75, 0xffff0000, v5
	v_pk_add_f32 v[64:65], v[64:65], v[80:81]
	v_pk_add_f32 v[60:61], v[60:61], v[74:75]
	s_waitcnt vmcnt(0)
	v_mov_b32_e32 v4, v144
	v_mov_b32_e32 v5, v145
	v_lshlrev_b32_e32 v84, 16, v4
	v_and_b32_e32 v85, 0xffff0000, v4
	v_lshlrev_b32_e32 v78, 16, v5
	v_and_b32_e32 v79, 0xffff0000, v5
	v_pk_add_f32 v[64:65], v[64:65], v[84:85]
	v_pk_add_f32 v[60:61], v[60:61], v[78:79]
	s_waitcnt vmcnt(0)
	v_mov_b32_e32 v4, v146
	v_mov_b32_e32 v5, v147
	v_lshlrev_b32_e32 v86, 16, v4
	v_and_b32_e32 v87, 0xffff0000, v4
	v_lshlrev_b32_e32 v82, 16, v5
	v_and_b32_e32 v83, 0xffff0000, v5
	v_pk_add_f32 v[64:65], v[64:65], v[86:87]
	v_pk_add_f32 v[60:61], v[60:61], v[82:83]
	s_waitcnt vmcnt(0)
	v_mov_b32_e32 v94, v156
	v_mov_b32_e32 v95, v157
	v_mov_b32_e32 v96, v158
	v_mov_b32_e32 v97, v159
	v_mov_b32_e32 v4, v152
	v_mov_b32_e32 v5, v153
	v_mov_b32_e32 v6, v154
	v_mov_b32_e32 v7, v155
	v_pk_mul_f32 v[68:69], v[94:95], 0.5 op_sel_hi:[1,0]
	v_pk_mul_f32 v[62:63], v[96:97], 0.5 op_sel_hi:[1,0]
	v_pk_fma_f32 v[4:5], v[64:65], v[68:69], v[4:5]
	v_pk_fma_f32 v[6:7], v[60:61], v[62:63], v[6:7]
	global_store_dwordx4 v[18:19], v[4:7], off offset:2048
	v_mul_f32_e32 v60, v5, v5
	v_mul_f32_e32 v62, v7, v7
	v_pk_fma_f32 v[60:61], v[4:5], v[4:5], v[60:61] op_sel_hi:[1,1,0]
	v_pk_fma_f32 v[62:63], v[6:7], v[6:7], v[62:63] op_sel_hi:[1,1,0]
	s_waitcnt vmcnt(0)
	v_mov_b32_e32 v12, v160
	v_mov_b32_e32 v13, v161
	v_lshlrev_b32_e32 v68, 16, v12
	v_and_b32_e32 v69, 0xffff0000, v12
	v_lshlrev_b32_e32 v64, 16, v13
	v_and_b32_e32 v65, 0xffff0000, v13
	v_pk_add_f32 v[68:69], v[68:69], 0 op_sel_hi:[1,0]
	v_pk_add_f32 v[64:65], v[64:65], 0 op_sel_hi:[1,0]
	s_waitcnt vmcnt(0)
	v_mov_b32_e32 v12, v162
	v_mov_b32_e32 v13, v163
	v_lshlrev_b32_e32 v70, 16, v12
	v_and_b32_e32 v71, 0xffff0000, v12
	v_lshlrev_b32_e32 v66, 16, v13
	v_and_b32_e32 v67, 0xffff0000, v13
	v_pk_add_f32 v[68:69], v[68:69], v[70:71]
	v_pk_add_f32 v[64:65], v[64:65], v[66:67]
	s_waitcnt vmcnt(0)
; DEVI void ctx_combine_phase(const Params& p, int l, int gi, float coef, int ln, int lwhich) {
;     ...
;       for (int sl = 0; sl < 7; ++sl) {
;         const uint2 w = *((const uint2*)(PS + ((size_t)sl * TC + rc) * D) + lane + 64 * j);
;         sum[0] += __uint_as_float(w.x << 16); sum[1] += __uint_as_float(w.x & 0xffff0000u); sum[2] += __uint_as_float(w.y << 16); sum[3] += __uint_as_float(w.y & 0xffff0000u);
;       }
;       const f32x4 xo = x4[64 * j], gv = gate4[64 * j];
; #pragma unroll
;       for (int q = 0; q < 4; ++q) v[j][q] = xo[q] + coef * gv[q] * sum[q];
;       x4[64 * j] = v[j];
;       ss += (v[j][0] * v[j][0] + v[j][1] * v[j][1]) + (v[j][2] * v[j][2] + v[j][3] * v[j][3]);
;     }
;     if (ln >= 0) {
;       const f32x4* g4 = (const f32x4*)(p.in[6] + (size_t)(ln * 3 + lwhich) * D) + lane;
;       const f32x4* sh4 = (const f32x4*)(MOD + (size_t)((ln * 9 + 8) * 9 + lwhich * 3) * D) + lane;
;       const f32x4* sc4 = sh4 + D / 4;
;       const float rinv = rsqrtf(wave_sum(ss, lane) * (1.f / D) + 1e-6f);
;       uint2* o8 = (uint2*)(H + (size_t)(TL + rc) * D) + lane;
; #pragma unroll
;       for (int j = 0; j < 4; ++j) {
;         const f32x4 g = g4[64 * j], sh = sh4[64 * j], sc = sc4[64 * j];
	v_mov_b32_e32 v12, v164
	v_mov_b32_e32 v13, v165
	v_lshlrev_b32_e32 v72, 16, v12
	v_and_b32_e32 v73, 0xffff0000, v12
	v_lshlrev_b32_e32 v22, 16, v13
	v_and_b32_e32 v23, 0xffff0000, v13
	v_pk_add_f32 v[68:69], v[68:69], v[72:73]
	v_pk_add_f32 v[22:23], v[64:65], v[22:23]
	s_waitcnt vmcnt(0)
	v_mov_b32_e32 v12, v166
	v_mov_b32_e32 v13, v167
	v_lshlrev_b32_e32 v74, 16, v12
	v_and_b32_e32 v75, 0xffff0000, v12
	v_lshlrev_b32_e32 v52, 16, v13
	v_and_b32_e32 v53, 0xffff0000, v13
	v_pk_add_f32 v[68:69], v[68:69], v[74:75]
	v_pk_add_f32 v[22:23], v[22:23], v[52:53]
	s_waitcnt vmcnt(0)
	v_mov_b32_e32 v12, v168
	v_mov_b32_e32 v13, v169
	v_lshlrev_b32_e32 v76, 16, v12
	v_and_b32_e32 v77, 0xffff0000, v12
	v_lshlrev_b32_e32 v54, 16, v13
	v_and_b32_e32 v55, 0xffff0000, v13
	v_pk_add_f32 v[68:69], v[68:69], v[76:77]
	v_pk_add_f32 v[22:23], v[22:23], v[54:55]
	s_waitcnt vmcnt(0)
	v_mov_b32_e32 v12, v170
	v_mov_b32_e32 v13, v171
	v_lshlrev_b32_e32 v80, 16, v12
	v_and_b32_e32 v81, 0xffff0000, v12
	v_lshlrev_b32_e32 v56, 16, v13
	v_and_b32_e32 v57, 0xffff0000, v13
	v_pk_add_f32 v[68:69], v[68:69], v[80:81]
	v_pk_add_f32 v[22:23], v[22:23], v[56:57]
	v_lshl_add_u64 v[50:51], v[50:51], 0, s[26:27]
	s_waitcnt vmcnt(0)
	v_mov_b32_e32 v12, v172
	v_mov_b32_e32 v13, v173
	v_lshlrev_b32_e32 v82, 16, v12
	v_and_b32_e32 v83, 0xffff0000, v12
	v_lshlrev_b32_e32 v78, 16, v13
	v_and_b32_e32 v79, 0xffff0000, v13
	v_pk_add_f32 v[68:69], v[68:69], v[82:83]
	v_pk_add_f32 v[22:23], v[22:23], v[78:79]
	s_waitcnt vmcnt(0)
	global_load_dwordx4 v[100:103], v[48:49], off
	global_load_dwordx4 v[112:115], v[32:33], off
	global_load_dwordx4 v[116:119], v[34:35], off
	global_load_dwordx4 v[120:123], v[48:49], off offset:1024
	global_load_dwordx4 v[124:127], v[36:37], off
	global_load_dwordx4 v[128:131], v[38:39], off
	global_load_dwordx4 v[132:135], v[48:49], off offset:2048
	global_load_dwordx4 v[136:139], v[40:41], off
	global_load_dwordx4 v[140:143], v[42:43], off
	global_load_dwordx4 v[144:147], v[48:49], off offset:3072
	global_load_dwordx4 v[152:155], v[44:45], off
	global_load_dwordx4 v[156:159], v[46:47], off
	v_mov_b32_e32 v84, v180
	v_mov_b32_e32 v85, v181
	v_mov_b32_e32 v86, v182
	v_mov_b32_e32 v87, v183
	v_mov_b32_e32 v12, v176
	v_mov_b32_e32 v13, v177
	v_mov_b32_e32 v14, v178
	v_mov_b32_e32 v15, v179
	v_pk_mul_f32 v[70:71], v[84:85], 0.5 op_sel_hi:[1,0]
	v_pk_mul_f32 v[52:53], v[86:87], 0.5 op_sel_hi:[1,0]
	v_pk_fma_f32 v[12:13], v[68:69], v[70:71], v[12:13]
	v_pk_fma_f32 v[14:15], v[22:23], v[52:53], v[14:15]
	global_store_dwordx4 v[18:19], v[12:15], off offset:3072
	v_pk_mul_f32 v[18:19], v[12:13], v[12:13]
	v_pk_mul_f32 v[22:23], v[14:15], v[14:15]
	v_mov_b32_e32 v21, v18
	v_mov_b32_e32 v59, v19
	v_mov_b32_e32 v61, v22
	v_mov_b32_e32 v63, v23
	v_pk_add_f32 v[18:19], v[20:21], v[58:59]
	v_pk_add_f32 v[20:21], v[60:61], v[62:63]
	v_lshl_add_u64 v[52:53], v[30:31], 0, v[16:17]
	v_pk_add_f32 v[18:19], v[18:19], v[20:21]
	s_nop 0
	v_add_f32_e32 v18, v18, v19
	ds_bpermute_b32 v19, v88, v18
	s_waitcnt lgkmcnt(0)
	v_add_f32_e32 v18, v18, v19
	ds_bpermute_b32 v19, v89, v18
	s_waitcnt lgkmcnt(0)
	v_add_f32_e32 v18, v18, v19
	ds_bpermute_b32 v19, v90, v18
	s_waitcnt lgkmcnt(0)
	v_add_f32_e32 v18, v18, v19
	ds_bpermute_b32 v19, v91, v18
	s_waitcnt lgkmcnt(0)
	v_add_f32_e32 v18, v18, v19
	ds_bpermute_b32 v19, v92, v18
	s_waitcnt lgkmcnt(0)
	v_add_f32_e32 v18, v18, v19
	ds_bpermute_b32 v19, v93, v18
	s_waitcnt lgkmcnt(0)
	v_add_f32_e32 v18, v18, v19
	v_fmamk_f32 v18, v18, 0x3a800000, v230
	v_cmp_gt_f32_e32 vcc, s24, v18
	v_mul_f32_e32 v19, 0x4b800000, v18
	s_nop 0
	v_cndmask_b32_e32 v18, v18, v19, vcc
	v_rsq_f32_e32 v18, v18
	s_nop 0
	v_mul_f32_e32 v19, 0x45800000, v18
	v_cndmask_b32_e32 v25, v18, v19, vcc
	s_waitcnt vmcnt(0)
; DEVI unsigned pk_bf16(float lo, float hi) { unsigned r; asm volatile("v_cvt_pk_bf16_f32 %0, %1, %2" : "=v"(r) : "v"(lo), "v"(hi)); return r; }
; DEVI void ctx_combine_phase(const Params& p, int l, int gi, float coef, int ln, int lwhich) {
;     ...
; #pragma unroll
;       for (int j = 0; j < 4; ++j) {
;         const f32x4 g = g4[64 * j], sh = sh4[64 * j], sc = sc4[64 * j];
;         f32x4 y;
; #pragma unroll
;         for (int q = 0; q < 4; ++q) y[q] = v[j][q] * rinv * g[q] * (1.f + sc[q]) + sh[q];
;         uint2 o; o.x = pk_bf16(y[0], y[1]); o.y = pk_bf16(y[2], y[3]); o8[64 * j] = o;
;       }
	v_mov_b32_e32 v20, v100
	v_mov_b32_e32 v21, v101
	v_mov_b32_e32 v22, v102
	v_mov_b32_e32 v23, v103
	v_mov_b32_e32 v16, v112
	v_mov_b32_e32 v17, v113
	v_mov_b32_e32 v18, v114
	v_mov_b32_e32 v19, v115
	v_mov_b32_e32 v54, v116
	v_mov_b32_e32 v55, v117
	v_mov_b32_e32 v56, v118
	v_mov_b32_e32 v57, v119
	v_mul_f32_e32 v8, v8, v25
	v_mul_f32_e32 v9, v9, v25
	v_mul_f32_e32 v10, v10, v25
	v_mul_f32_e32 v11, v11, v25
	v_mul_f32_e32 v0, v0, v25
	v_mul_f32_e32 v1, v1, v25
	v_mul_f32_e32 v2, v2, v25
	v_mul_f32_e32 v3, v3, v25
	v_mul_f32_e32 v4, v4, v25
	v_mul_f32_e32 v12, v12, v25
	v_cmp_lt_i32_e32 vcc, s25, v24
	s_or_b64 s[6:7], vcc, s[6:7]
	v_mul_f32_e32 v8, v20, v8
	v_mul_f32_e32 v9, v21, v9
	v_add_f32_e32 v20, 1.0, v54
	v_fma_f32 v8, v20, v8, v16
	v_add_f32_e32 v16, 1.0, v55
	v_fma_f32 v9, v16, v9, v17
	v_mul_f32_e32 v10, v22, v10
	v_add_f32_e32 v16, 1.0, v56
	v_fma_f32 v10, v16, v10, v18
	v_mul_f32_e32 v11, v23, v11
	v_add_f32_e32 v16, 1.0, v57
	v_fmac_f32_e32 v19, v16, v11
	v_cvt_pk_bf16_f32 v8, v8, v9
	v_cvt_pk_bf16_f32 v9, v10, v19
	global_store_dwordx2 v[52:53], v[8:9], off
	s_nop 1
	v_mov_b32_e32 v8, v120
	v_mov_b32_e32 v9, v121
	v_mov_b32_e32 v10, v122
	v_mov_b32_e32 v11, v123
	v_mov_b32_e32 v16, v124
	v_mov_b32_e32 v17, v125
	v_mov_b32_e32 v18, v126
	v_mov_b32_e32 v19, v127
	v_mov_b32_e32 v20, v128
	v_mov_b32_e32 v21, v129
	v_mov_b32_e32 v22, v130
	v_mov_b32_e32 v23, v131
	s_nop 0
	v_mul_f32_e32 v0, v8, v0
	v_mul_f32_e32 v1, v9, v1
	v_add_f32_e32 v8, 1.0, v20
	v_fma_f32 v0, v8, v0, v16
	v_add_f32_e32 v8, 1.0, v21
	v_fma_f32 v1, v8, v1, v17
	v_mul_f32_e32 v2, v10, v2
	v_add_f32_e32 v8, 1.0, v22
	v_fma_f32 v2, v8, v2, v18
	v_mul_f32_e32 v3, v11, v3
	v_add_f32_e32 v8, 1.0, v23
	v_fmac_f32_e32 v19, v8, v3
	v_cvt_pk_bf16_f32 v0, v0, v1
	v_cvt_pk_bf16_f32 v1, v2, v19
	global_store_dwordx2 v[52:53], v[0:1], off offset:512
	s_nop 1
	v_mov_b32_e32 v0, v132
	v_mov_b32_e32 v1, v133
	v_mov_b32_e32 v2, v134
	v_mov_b32_e32 v3, v135
	v_mov_b32_e32 v8, v136
	v_mov_b32_e32 v9, v137
	v_mov_b32_e32 v10, v138
	v_mov_b32_e32 v11, v139
	v_mov_b32_e32 v16, v140
	v_mov_b32_e32 v17, v141
	v_mov_b32_e32 v18, v142
	v_mov_b32_e32 v19, v143
	s_nop 0
	v_mul_f32_e32 v0, v4, v0
	v_add_f32_e32 v4, 1.0, v16
	v_fma_f32 v0, v0, v4, v8
	v_mul_f32_e32 v4, v5, v25
	v_mul_f32_e32 v1, v4, v1
	v_add_f32_e32 v4, 1.0, v17
	v_fma_f32 v1, v1, v4, v9
	v_mul_f32_e32 v4, v6, v25
	v_mul_f32_e32 v2, v4, v2
	v_add_f32_e32 v4, 1.0, v18
	v_fma_f32 v2, v2, v4, v10
	v_mul_f32_e32 v4, v7, v25
	v_mul_f32_e32 v3, v4, v3
	v_add_f32_e32 v4, 1.0, v19
	v_fmac_f32_e32 v11, v3, v4
	v_cvt_pk_bf16_f32 v0, v0, v1
	v_cvt_pk_bf16_f32 v1, v2, v11
	global_store_dwordx2 v[52:53], v[0:1], off offset:1024
	s_nop 1
	v_mov_b32_e32 v0, v144
	v_mov_b32_e32 v1, v145
	v_mov_b32_e32 v2, v146
	v_mov_b32_e32 v3, v147
	v_mov_b32_e32 v4, v152
	v_mov_b32_e32 v5, v153
	v_mov_b32_e32 v6, v154
	v_mov_b32_e32 v7, v155
	v_mov_b32_e32 v8, v156
	v_mov_b32_e32 v9, v157
	v_mov_b32_e32 v10, v158
	v_mov_b32_e32 v11, v159
	s_nop 0
	v_mul_f32_e32 v0, v12, v0
	v_add_f32_e32 v8, 1.0, v8
	v_fma_f32 v0, v0, v8, v4
	v_mul_f32_e32 v4, v13, v25
	v_mul_f32_e32 v1, v4, v1
	v_add_f32_e32 v4, 1.0, v9
	v_fma_f32 v1, v1, v4, v5
	v_mul_f32_e32 v4, v14, v25
	v_mul_f32_e32 v2, v4, v2
	v_add_f32_e32 v4, 1.0, v10
	v_fma_f32 v2, v2, v4, v6
	v_mul_f32_e32 v4, v15, v25
	v_mul_f32_e32 v3, v4, v3
	v_add_f32_e32 v4, 1.0, v11
	v_fmac_f32_e32 v7, v3, v4
	v_cvt_pk_bf16_f32 v0, v0, v1
	v_cvt_pk_bf16_f32 v1, v2, v7
	global_store_dwordx2 v[52:53], v[0:1], off offset:1536
	s_andn2_b64 exec, exec, s[6:7]
	s_cbranch_execnz .LBB0_1040

; DEVI void ctx_combine_phase(const Params& p, int l, int gi, float coef, int ln, int lwhich) {
;     ...
;   for (int rc = gw; rc < TC; rc += NW) {
;     f32x4* x4 = (f32x4*)(X + (size_t)(TL + rc) * D) + lane;
;     f32x4 v[4]; float ss = 0.f;
; #pragma unroll
;     for (int j = 0; j < 4; ++j) {
;       f32x4 sum = {0.f, 0.f, 0.f, 0.f};
; #pragma unroll
;       for (int sl = 0; sl < 7; ++sl) {
;         const uint2 w = *((const uint2*)(PS + ((size_t)sl * TC + rc) * D) + lane + 64 * j);
;         sum[0] += __uint_as_float(w.x << 16); sum[1] += __uint_as_float(w.x & 0xffff0000u); sum[2] += __uint_as_float(w.y << 16); sum[3] += __uint_as_float(w.y & 0xffff0000u);
;       }
;       const f32x4 xo = x4[64 * j], gv = gate4[64 * j];
; #pragma unroll
;       for (int q = 0; q < 4; ++q) v[j][q] = xo[q] + coef * gv[q] * sum[q];
;       x4[64 * j] = v[j];
;       ss += (v[j][0] * v[j][0] + v[j][1] * v[j][1]) + (v[j][2] * v[j][2] + v[j][3] * v[j][3]);
.LBB0_1929:
	v_add_co_u32_e32 v12, vcc, 0xfe800000, v50
	v_add_u32_e32 v16, 0x8000, v24
	s_nop 0
	v_addc_co_u32_e32 v13, vcc, -1, v51, vcc
	v_add_co_u32_e32 v14, vcc, 0xfec00000, v50
	v_ashrrev_i32_e32 v17, 31, v16
	s_nop 0
	v_addc_co_u32_e32 v15, vcc, -1, v51, vcc
	v_add_co_u32_e32 v22, vcc, 0xff000000, v50
	v_lshlrev_b64 v[0:1], 12, v[16:17]
	s_nop 0
	v_addc_co_u32_e32 v23, vcc, -1, v51, vcc
	v_add_co_u32_e32 v52, vcc, 0xff400000, v50
	v_lshl_add_u64 v[18:19], v[28:29], 0, v[0:1]
	s_nop 0
	v_addc_co_u32_e32 v53, vcc, -1, v51, vcc
	v_add_co_u32_e32 v54, vcc, 0xff800000, v50
	global_load_dwordx2 v[20:21], v[52:53], off offset:-1540
	s_nop 0
	v_addc_co_u32_e32 v55, vcc, -1, v51, vcc
	global_load_dwordx2 v[56:57], v[54:55], off offset:-1540
	global_load_dwordx2 v[0:1], v[12:13], off offset:-1540
	global_load_dwordx2 v[4:5], v[14:15], off offset:-1540
	global_load_dwordx2 v[10:11], v[22:23], off offset:-1540
	v_add_co_u32_e32 v98, vcc, 0xffc00000, v50
	s_nop 1
	v_addc_co_u32_e32 v99, vcc, -1, v51, vcc
	global_load_dwordx2 v[100:101], v[98:99], off offset:-1540
	global_load_dwordx2 v[102:103], v[50:51], off offset:-1540
	global_load_dwordx4 v[104:107], v[18:19], off
	global_load_dwordx4 v[108:111], v[26:27], off
	global_load_dwordx2 v[112:113], v[12:13], off offset:-1028
	global_load_dwordx2 v[114:115], v[14:15], off offset:-1028
	global_load_dwordx2 v[116:117], v[22:23], off offset:-1028
	global_load_dwordx2 v[118:119], v[52:53], off offset:-1028
	global_load_dwordx2 v[120:121], v[54:55], off offset:-1028
	global_load_dwordx2 v[122:123], v[98:99], off offset:-1028
	global_load_dwordx2 v[124:125], v[50:51], off offset:-1028
	global_load_dwordx4 v[126:129], v[18:19], off offset:1024
	global_load_dwordx4 v[130:133], v[26:27], off offset:1024
	global_load_dwordx2 v[134:135], v[12:13], off offset:-516
	global_load_dwordx2 v[136:137], v[14:15], off offset:-516
	global_load_dwordx2 v[138:139], v[22:23], off offset:-516
	global_load_dwordx2 v[140:141], v[52:53], off offset:-516
	global_load_dwordx2 v[142:143], v[54:55], off offset:-516
	global_load_dwordx2 v[144:145], v[98:99], off offset:-516
	global_load_dwordx2 v[146:147], v[50:51], off offset:-516
	global_load_dwordx4 v[152:155], v[18:19], off offset:2048
	global_load_dwordx4 v[156:159], v[26:27], off offset:2048
	global_load_dwordx2 v[160:161], v[12:13], off offset:-4
	global_load_dwordx2 v[162:163], v[14:15], off offset:-4
	global_load_dwordx2 v[164:165], v[22:23], off offset:-4
	global_load_dwordx2 v[166:167], v[52:53], off offset:-4
	global_load_dwordx2 v[168:169], v[54:55], off offset:-4
	global_load_dwordx2 v[170:171], v[98:99], off offset:-4
	global_load_dwordx2 v[172:173], v[50:51], off offset:-4
	global_load_dwordx4 v[176:179], v[18:19], off offset:3072
	global_load_dwordx4 v[180:183], v[26:27], off offset:3072
	v_lshlrev_b64 v[16:17], 11, v[16:17]
	v_add_u32_e32 v24, s2, v24
	s_waitcnt vmcnt(4)
	v_lshlrev_b32_e32 v58, 16, v20
	v_and_b32_e32 v59, 0xffff0000, v20
	v_lshlrev_b32_e32 v20, 16, v21
	s_waitcnt vmcnt(3)
	v_lshlrev_b32_e32 v68, 16, v56
	v_and_b32_e32 v69, 0xffff0000, v56
	v_add_co_u32_e32 v56, vcc, 0xffc00000, v50
	v_lshlrev_b32_e32 v70, 16, v57
	v_and_b32_e32 v71, 0xffff0000, v57
	v_addc_co_u32_e32 v57, vcc, -1, v51, vcc
	v_and_b32_e32 v21, 0xffff0000, v21
	s_waitcnt vmcnt(0)
	v_mov_b32_e32 v60, v100
	v_mov_b32_e32 v61, v101
	v_lshlrev_b32_e32 v72, 16, v60
	v_and_b32_e32 v73, 0xffff0000, v60
	v_lshlrev_b32_e32 v74, 16, v61
	v_and_b32_e32 v75, 0xffff0000, v61
	v_lshlrev_b32_e32 v2, 16, v0
	v_and_b32_e32 v3, 0xffff0000, v0
	v_lshlrev_b32_e32 v0, 16, v1
	v_and_b32_e32 v1, 0xffff0000, v1
	v_lshlrev_b32_e32 v6, 16, v4
	v_and_b32_e32 v7, 0xffff0000, v4
	v_lshlrev_b32_e32 v4, 16, v5
	v_and_b32_e32 v5, 0xffff0000, v5
	v_pk_add_f32 v[2:3], v[2:3], 0 op_sel_hi:[1,0]
	v_pk_add_f32 v[0:1], v[0:1], 0 op_sel_hi:[1,0]
	v_lshlrev_b32_e32 v8, 16, v10
	v_and_b32_e32 v9, 0xffff0000, v10
	v_lshlrev_b32_e32 v10, 16, v11
	v_and_b32_e32 v11, 0xffff0000, v11
	v_pk_add_f32 v[2:3], v[2:3], v[6:7]
	v_pk_add_f32 v[0:1], v[0:1], v[4:5]
	v_pk_add_f32 v[2:3], v[2:3], v[8:9]
	v_pk_add_f32 v[0:1], v[0:1], v[10:11]
	v_pk_add_f32 v[2:3], v[2:3], v[58:59]
	v_pk_add_f32 v[0:1], v[0:1], v[20:21]
	v_pk_add_f32 v[2:3], v[2:3], v[68:69]
	v_pk_add_f32 v[0:1], v[0:1], v[70:71]
	v_pk_add_f32 v[2:3], v[2:3], v[72:73]
	v_pk_add_f32 v[0:1], v[0:1], v[74:75]
	s_waitcnt vmcnt(0)
	v_mov_b32_e32 v60, v102
	v_mov_b32_e32 v61, v103
	v_lshlrev_b32_e32 v76, 16, v60
	v_and_b32_e32 v77, 0xffff0000, v60
	v_lshlrev_b32_e32 v78, 16, v61
	v_and_b32_e32 v79, 0xffff0000, v61
	v_pk_add_f32 v[2:3], v[2:3], v[76:77]
	v_pk_add_f32 v[0:1], v[0:1], v[78:79]
	s_waitcnt vmcnt(0)
	v_mov_b32_e32 v64, v108
	v_mov_b32_e32 v65, v109
	v_mov_b32_e32 v66, v110
	v_mov_b32_e32 v67, v111
	v_mov_b32_e32 v60, v104
	v_mov_b32_e32 v61, v105
	v_mov_b32_e32 v62, v106
	v_mov_b32_e32 v63, v107
	v_pk_fma_f32 v[8:9], v[2:3], v[64:65], v[60:61]
	v_pk_fma_f32 v[10:11], v[0:1], v[66:67], v[62:63]
	v_mov_b32_e32 v2, v9
	v_mov_b32_e32 v3, v11
	v_mov_b32_e32 v0, v8
	v_mov_b32_e32 v1, v10
	v_pk_mul_f32 v[2:3], v[2:3], v[2:3]
	global_store_dwordx4 v[18:19], v[8:11], off
	v_pk_fma_f32 v[0:1], v[0:1], v[0:1], v[2:3]
	s_nop 0
	v_pk_add_f32 v[20:21], v[0:1], v[0:1] op_sel:[0,1] op_sel_hi:[1,0]
	s_waitcnt vmcnt(0)
	v_mov_b32_e32 v0, v112
	v_mov_b32_e32 v1, v113
	v_lshlrev_b32_e32 v58, 16, v0
	v_and_b32_e32 v59, 0xffff0000, v0
	v_lshlrev_b32_e32 v4, 16, v1
	v_and_b32_e32 v5, 0xffff0000, v1
	v_pk_add_f32 v[58:59], v[58:59], 0 op_sel_hi:[1,0]
	v_pk_add_f32 v[4:5], v[4:5], 0 op_sel_hi:[1,0]
	s_waitcnt vmcnt(0)
; DEVI void ctx_combine_phase(const Params& p, int l, int gi, float coef, int ln, int lwhich) {
;     ...
;     for (int j = 0; j < 4; ++j) {
;       f32x4 sum = {0.f, 0.f, 0.f, 0.f};
; #pragma unroll
;       for (int sl = 0; sl < 7; ++sl) {
;         const uint2 w = *((const uint2*)(PS + ((size_t)sl * TC + rc) * D) + lane + 64 * j);
;         sum[0] += __uint_as_float(w.x << 16); sum[1] += __uint_as_float(w.x & 0xffff0000u); sum[2] += __uint_as_float(w.y << 16); sum[3] += __uint_as_float(w.y & 0xffff0000u);
;       }
;       const f32x4 xo = x4[64 * j], gv = gate4[64 * j];
; #pragma unroll
;       for (int q = 0; q < 4; ++q) v[j][q] = xo[q] + coef * gv[q] * sum[q];
;       x4[64 * j] = v[j];
;       ss += (v[j][0] * v[j][0] + v[j][1] * v[j][1]) + (v[j][2] * v[j][2] + v[j][3] * v[j][3]);
	v_mov_b32_e32 v0, v114
	v_mov_b32_e32 v1, v115
	v_lshlrev_b32_e32 v62, 16, v0
	v_and_b32_e32 v63, 0xffff0000, v0
	v_lshlrev_b32_e32 v6, 16, v1
	v_and_b32_e32 v7, 0xffff0000, v1
	v_pk_add_f32 v[58:59], v[58:59], v[62:63]
	v_pk_add_f32 v[4:5], v[4:5], v[6:7]
	s_waitcnt vmcnt(0)
	v_mov_b32_e32 v0, v116
	v_mov_b32_e32 v1, v117
	v_lshlrev_b32_e32 v66, 16, v0
	v_and_b32_e32 v67, 0xffff0000, v0
	v_lshlrev_b32_e32 v60, 16, v1
	v_and_b32_e32 v61, 0xffff0000, v1
	v_pk_add_f32 v[58:59], v[58:59], v[66:67]
	v_pk_add_f32 v[4:5], v[4:5], v[60:61]
	s_waitcnt vmcnt(0)
	v_mov_b32_e32 v0, v118
	v_mov_b32_e32 v1, v119
	v_lshlrev_b32_e32 v70, 16, v0
	v_and_b32_e32 v71, 0xffff0000, v0
	v_lshlrev_b32_e32 v64, 16, v1
	v_and_b32_e32 v65, 0xffff0000, v1
	v_pk_add_f32 v[58:59], v[58:59], v[70:71]
	v_pk_add_f32 v[4:5], v[4:5], v[64:65]
	s_waitcnt vmcnt(0)
	v_mov_b32_e32 v0, v120
	v_mov_b32_e32 v1, v121
	v_lshlrev_b32_e32 v74, 16, v0
	v_and_b32_e32 v75, 0xffff0000, v0
	v_lshlrev_b32_e32 v68, 16, v1
	v_and_b32_e32 v69, 0xffff0000, v1
	v_pk_add_f32 v[58:59], v[58:59], v[74:75]
	v_pk_add_f32 v[4:5], v[4:5], v[68:69]
	s_waitcnt vmcnt(0)
	v_mov_b32_e32 v0, v122
	v_mov_b32_e32 v1, v123
	v_lshlrev_b32_e32 v78, 16, v0
	v_and_b32_e32 v79, 0xffff0000, v0
	v_lshlrev_b32_e32 v72, 16, v1
	v_and_b32_e32 v73, 0xffff0000, v1
	v_pk_add_f32 v[58:59], v[58:59], v[78:79]
	v_pk_add_f32 v[4:5], v[4:5], v[72:73]
	s_waitcnt vmcnt(0)
	v_mov_b32_e32 v0, v124
	v_mov_b32_e32 v1, v125
	v_lshlrev_b32_e32 v80, 16, v0
	v_and_b32_e32 v81, 0xffff0000, v0
	v_lshlrev_b32_e32 v76, 16, v1
	v_and_b32_e32 v77, 0xffff0000, v1
	v_pk_add_f32 v[58:59], v[58:59], v[80:81]
	v_pk_add_f32 v[4:5], v[4:5], v[76:77]
	s_waitcnt vmcnt(0)
	v_mov_b32_e32 v82, v130
	v_mov_b32_e32 v83, v131
	v_mov_b32_e32 v84, v132
	v_mov_b32_e32 v85, v133
	v_mov_b32_e32 v0, v126
	v_mov_b32_e32 v1, v127
	v_mov_b32_e32 v2, v128
	v_mov_b32_e32 v3, v129
	v_pk_fma_f32 v[0:1], v[58:59], v[82:83], v[0:1]
	v_pk_fma_f32 v[2:3], v[4:5], v[84:85], v[2:3]
	v_mov_b32_e32 v6, v1
	v_mov_b32_e32 v7, v3
	v_mov_b32_e32 v4, v0
	v_mov_b32_e32 v5, v2
	v_pk_mul_f32 v[6:7], v[6:7], v[6:7]
	global_store_dwordx4 v[18:19], v[0:3], off offset:1024
	v_pk_fma_f32 v[4:5], v[4:5], v[4:5], v[6:7]
	s_nop 0
	v_pk_add_f32 v[58:59], v[4:5], v[4:5] op_sel:[0,1] op_sel_hi:[1,0]
	s_waitcnt vmcnt(0)
	v_mov_b32_e32 v4, v134
	v_mov_b32_e32 v5, v135
	v_lshlrev_b32_e32 v64, 16, v4
	v_and_b32_e32 v65, 0xffff0000, v4
	v_lshlrev_b32_e32 v60, 16, v5
	v_and_b32_e32 v61, 0xffff0000, v5
	v_pk_add_f32 v[64:65], v[64:65], 0 op_sel_hi:[1,0]
	v_pk_add_f32 v[60:61], v[60:61], 0 op_sel_hi:[1,0]
	s_waitcnt vmcnt(0)
	v_mov_b32_e32 v4, v136
	v_mov_b32_e32 v5, v137
	v_lshlrev_b32_e32 v68, 16, v4
	v_and_b32_e32 v69, 0xffff0000, v4
	v_lshlrev_b32_e32 v62, 16, v5
	v_and_b32_e32 v63, 0xffff0000, v5
	v_pk_add_f32 v[64:65], v[64:65], v[68:69]
	v_pk_add_f32 v[60:61], v[60:61], v[62:63]
	s_waitcnt vmcnt(0)
	v_mov_b32_e32 v4, v138
	v_mov_b32_e32 v5, v139
	v_lshlrev_b32_e32 v72, 16, v4
	v_and_b32_e32 v73, 0xffff0000, v4
	v_lshlrev_b32_e32 v66, 16, v5
	v_and_b32_e32 v67, 0xffff0000, v5
	v_pk_add_f32 v[64:65], v[64:65], v[72:73]
	v_pk_add_f32 v[60:61], v[60:61], v[66:67]
	s_waitcnt vmcnt(0)
	v_mov_b32_e32 v4, v140
	v_mov_b32_e32 v5, v141
	v_lshlrev_b32_e32 v76, 16, v4
	v_and_b32_e32 v77, 0xffff0000, v4
	v_lshlrev_b32_e32 v70, 16, v5
	v_and_b32_e32 v71, 0xffff0000, v5
	v_pk_add_f32 v[64:65], v[64:65], v[76:77]
	v_pk_add_f32 v[60:61], v[60:61], v[70:71]
	s_waitcnt vmcnt(0)
	v_mov_b32_e32 v4, v142
	v_mov_b32_e32 v5, v143
	v_lshlrev_b32_e32 v80, 16, v4
	v_and_b32_e32 v81, 0xffff0000, v4
	v_lshlrev_b32_e32 v74, 16, v5
	v_and_b32_e32 v75, 0xffff0000, v5
	v_pk_add_f32 v[64:65], v[64:65], v[80:81]
	v_pk_add_f32 v[60:61], v[60:61], v[74:75]
	s_waitcnt vmcnt(0)
	v_mov_b32_e32 v4, v144
	v_mov_b32_e32 v5, v145
	v_lshlrev_b32_e32 v84, 16, v4
	v_and_b32_e32 v85, 0xffff0000, v4
	v_lshlrev_b32_e32 v78, 16, v5
	v_and_b32_e32 v79, 0xffff0000, v5
	v_pk_add_f32 v[64:65], v[64:65], v[84:85]
	v_pk_add_f32 v[60:61], v[60:61], v[78:79]
	s_waitcnt vmcnt(0)
	v_mov_b32_e32 v4, v146
	v_mov_b32_e32 v5, v147
	v_lshlrev_b32_e32 v86, 16, v4
	v_and_b32_e32 v87, 0xffff0000, v4
	v_lshlrev_b32_e32 v82, 16, v5
	v_and_b32_e32 v83, 0xffff0000, v5
	v_pk_add_f32 v[64:65], v[64:65], v[86:87]
	v_pk_add_f32 v[60:61], v[60:61], v[82:83]
	s_waitcnt vmcnt(0)
	v_mov_b32_e32 v94, v156
	v_mov_b32_e32 v95, v157
	v_mov_b32_e32 v96, v158
	v_mov_b32_e32 v97, v159
	v_mov_b32_e32 v4, v152
	v_mov_b32_e32 v5, v153
	v_mov_b32_e32 v6, v154
	v_mov_b32_e32 v7, v155
	v_pk_fma_f32 v[4:5], v[64:65], v[94:95], v[4:5]
	v_pk_fma_f32 v[6:7], v[60:61], v[96:97], v[6:7]
	global_store_dwordx4 v[18:19], v[4:7], off offset:2048
	v_mul_f32_e32 v60, v5, v5
	v_mul_f32_e32 v62, v7, v7
	v_pk_fma_f32 v[60:61], v[4:5], v[4:5], v[60:61] op_sel_hi:[1,1,0]
	v_pk_fma_f32 v[62:63], v[6:7], v[6:7], v[62:63] op_sel_hi:[1,1,0]
	s_waitcnt vmcnt(0)
	v_mov_b32_e32 v12, v160
	v_mov_b32_e32 v13, v161
	v_lshlrev_b32_e32 v68, 16, v12
	v_and_b32_e32 v69, 0xffff0000, v12
	v_lshlrev_b32_e32 v64, 16, v13
	v_and_b32_e32 v65, 0xffff0000, v13
	v_pk_add_f32 v[68:69], v[68:69], 0 op_sel_hi:[1,0]
	v_pk_add_f32 v[64:65], v[64:65], 0 op_sel_hi:[1,0]
	s_waitcnt vmcnt(0)
	v_mov_b32_e32 v12, v162
	v_mov_b32_e32 v13, v163
	v_lshlrev_b32_e32 v70, 16, v12
	v_and_b32_e32 v71, 0xffff0000, v12
	v_lshlrev_b32_e32 v66, 16, v13
	v_and_b32_e32 v67, 0xffff0000, v13
	v_pk_add_f32 v[68:69], v[68:69], v[70:71]
	v_pk_add_f32 v[64:65], v[64:65], v[66:67]
	s_waitcnt vmcnt(0)
	v_mov_b32_e32 v12, v164
	v_mov_b32_e32 v13, v165
	v_lshlrev_b32_e32 v72, 16, v12
	v_and_b32_e32 v73, 0xffff0000, v12
	v_lshlrev_b32_e32 v22, 16, v13
	v_and_b32_e32 v23, 0xffff0000, v13
	v_pk_add_f32 v[68:69], v[68:69], v[72:73]
	v_pk_add_f32 v[22:23], v[64:65], v[22:23]
	s_waitcnt vmcnt(0)
; DEVI unsigned pk_bf16(float lo, float hi) { unsigned r; asm volatile("v_cvt_pk_bf16_f32 %0, %1, %2" : "=v"(r) : "v"(lo), "v"(hi)); return r; }
; DEVI void ctx_combine_phase(const Params& p, int l, int gi, float coef, int ln, int lwhich) {
;     ...
;       for (int sl = 0; sl < 7; ++sl) {
;         const uint2 w = *((const uint2*)(PS + ((size_t)sl * TC + rc) * D) + lane + 64 * j);
;         sum[0] += __uint_as_float(w.x << 16); sum[1] += __uint_as_float(w.x & 0xffff0000u); sum[2] += __uint_as_float(w.y << 16); sum[3] += __uint_as_float(w.y & 0xffff0000u);
;       }
;       const f32x4 xo = x4[64 * j], gv = gate4[64 * j];
; #pragma unroll
;       for (int q = 0; q < 4; ++q) v[j][q] = xo[q] + coef * gv[q] * sum[q];
;       x4[64 * j] = v[j];
;       ss += (v[j][0] * v[j][0] + v[j][1] * v[j][1]) + (v[j][2] * v[j][2] + v[j][3] * v[j][3]);
;     }
;     if (ln >= 0) {
;       const f32x4* g4 = (const f32x4*)(p.in[6] + (size_t)(ln * 3 + lwhich) * D) + lane;
;       const f32x4* sh4 = (const f32x4*)(MOD + (size_t)((ln * 9 + 8) * 9 + lwhich * 3) * D) + lane;
;       const f32x4* sc4 = sh4 + D / 4;
;       const float rinv = rsqrtf(wave_sum(ss, lane) * (1.f / D) + 1e-6f);
;       uint2* o8 = (uint2*)(H + (size_t)(TL + rc) * D) + lane;
; #pragma unroll
;       for (int j = 0; j < 4; ++j) {
;         const f32x4 g = g4[64 * j], sh = sh4[64 * j], sc = sc4[64 * j];
;         f32x4 y;
; #pragma unroll
;         for (int q = 0; q < 4; ++q) y[q] = v[j][q] * rinv * g[q] * (1.f + sc[q]) + sh[q];
;         uint2 o; o.x = pk_bf16(y[0], y[1]); o.y = pk_bf16(y[2], y[3]); o8[64 * j] = o;
;       }
	v_mov_b32_e32 v12, v166
	v_mov_b32_e32 v13, v167
	v_lshlrev_b32_e32 v74, 16, v12
	v_and_b32_e32 v75, 0xffff0000, v12
	v_lshlrev_b32_e32 v52, 16, v13
	v_and_b32_e32 v53, 0xffff0000, v13
	v_pk_add_f32 v[68:69], v[68:69], v[74:75]
	v_pk_add_f32 v[22:23], v[22:23], v[52:53]
	v_lshl_add_u64 v[52:53], v[30:31], 0, v[16:17]
	s_waitcnt vmcnt(0)
	v_mov_b32_e32 v12, v168
	v_mov_b32_e32 v13, v169
	v_lshlrev_b32_e32 v76, 16, v12
	v_and_b32_e32 v77, 0xffff0000, v12
	v_lshlrev_b32_e32 v54, 16, v13
	v_and_b32_e32 v55, 0xffff0000, v13
	v_pk_add_f32 v[68:69], v[68:69], v[76:77]
	v_pk_add_f32 v[22:23], v[22:23], v[54:55]
	s_waitcnt vmcnt(0)
	v_mov_b32_e32 v12, v170
	v_mov_b32_e32 v13, v171
	v_lshlrev_b32_e32 v80, 16, v12
	v_and_b32_e32 v81, 0xffff0000, v12
	v_lshlrev_b32_e32 v56, 16, v13
	v_and_b32_e32 v57, 0xffff0000, v13
	v_pk_add_f32 v[68:69], v[68:69], v[80:81]
	v_pk_add_f32 v[22:23], v[22:23], v[56:57]
	v_lshl_add_u64 v[50:51], v[50:51], 0, s[10:11]
	s_waitcnt vmcnt(0)
	v_mov_b32_e32 v12, v172
	v_mov_b32_e32 v13, v173
	v_lshlrev_b32_e32 v82, 16, v12
	v_and_b32_e32 v83, 0xffff0000, v12
	v_lshlrev_b32_e32 v78, 16, v13
	v_and_b32_e32 v79, 0xffff0000, v13
	v_pk_add_f32 v[68:69], v[68:69], v[82:83]
	v_pk_add_f32 v[22:23], v[22:23], v[78:79]
	s_waitcnt vmcnt(0)
	global_load_dwordx4 v[100:103], v[48:49], off
	global_load_dwordx4 v[112:115], v[32:33], off
	global_load_dwordx4 v[116:119], v[34:35], off
	global_load_dwordx4 v[120:123], v[48:49], off offset:1024
	global_load_dwordx4 v[124:127], v[36:37], off
	global_load_dwordx4 v[128:131], v[38:39], off
	global_load_dwordx4 v[132:135], v[48:49], off offset:2048
	global_load_dwordx4 v[136:139], v[40:41], off
	global_load_dwordx4 v[140:143], v[42:43], off
	global_load_dwordx4 v[144:147], v[48:49], off offset:3072
	global_load_dwordx4 v[152:155], v[44:45], off
	global_load_dwordx4 v[156:159], v[46:47], off
	v_mov_b32_e32 v84, v180
	v_mov_b32_e32 v85, v181
	v_mov_b32_e32 v86, v182
	v_mov_b32_e32 v87, v183
	v_mov_b32_e32 v12, v176
	v_mov_b32_e32 v13, v177
	v_mov_b32_e32 v14, v178
	v_mov_b32_e32 v15, v179
	v_pk_fma_f32 v[12:13], v[68:69], v[84:85], v[12:13]
	v_pk_fma_f32 v[14:15], v[22:23], v[86:87], v[14:15]
	global_store_dwordx4 v[18:19], v[12:15], off offset:3072
	v_pk_mul_f32 v[18:19], v[12:13], v[12:13]
	v_pk_mul_f32 v[22:23], v[14:15], v[14:15]
	v_mov_b32_e32 v21, v18
	v_mov_b32_e32 v59, v19
	v_mov_b32_e32 v61, v22
	v_mov_b32_e32 v63, v23
	v_pk_add_f32 v[18:19], v[20:21], v[58:59]
	v_pk_add_f32 v[20:21], v[60:61], v[62:63]
	s_nop 0
	v_pk_add_f32 v[18:19], v[18:19], v[20:21]
	s_nop 0
	v_add_f32_e32 v18, v18, v19
	ds_bpermute_b32 v19, v88, v18
	s_waitcnt lgkmcnt(0)
	v_add_f32_e32 v18, v18, v19
	ds_bpermute_b32 v19, v89, v18
	s_waitcnt lgkmcnt(0)
	v_add_f32_e32 v18, v18, v19
	ds_bpermute_b32 v19, v90, v18
	s_waitcnt lgkmcnt(0)
	v_add_f32_e32 v18, v18, v19
	ds_bpermute_b32 v19, v91, v18
	s_waitcnt lgkmcnt(0)
	v_add_f32_e32 v18, v18, v19
	ds_bpermute_b32 v19, v92, v18
	s_waitcnt lgkmcnt(0)
	v_add_f32_e32 v18, v18, v19
	ds_bpermute_b32 v19, v93, v18
	s_waitcnt lgkmcnt(0)
	v_add_f32_e32 v18, v18, v19
	v_fmamk_f32 v18, v18, 0x3a800000, v230
	v_cmp_gt_f32_e32 vcc, s8, v18
	v_mul_f32_e32 v19, 0x4b800000, v18
	s_nop 0
	v_cndmask_b32_e32 v18, v18, v19, vcc
	v_rsq_f32_e32 v18, v18
	s_nop 0
	v_mul_f32_e32 v19, 0x45800000, v18
	v_cndmask_b32_e32 v25, v18, v19, vcc
	s_waitcnt vmcnt(0)
	v_mov_b32_e32 v20, v100
	v_mov_b32_e32 v21, v101
	v_mov_b32_e32 v22, v102
	v_mov_b32_e32 v23, v103
	v_mov_b32_e32 v16, v112
	v_mov_b32_e32 v17, v113
	v_mov_b32_e32 v18, v114
	v_mov_b32_e32 v19, v115
	v_mov_b32_e32 v54, v116
	v_mov_b32_e32 v55, v117
	v_mov_b32_e32 v56, v118
	v_mov_b32_e32 v57, v119
	v_mul_f32_e32 v8, v8, v25
	v_mul_f32_e32 v9, v9, v25
	v_mul_f32_e32 v10, v10, v25
	v_mul_f32_e32 v11, v11, v25
	v_mul_f32_e32 v0, v0, v25
	v_mul_f32_e32 v1, v1, v25
	v_mul_f32_e32 v2, v2, v25
	v_mul_f32_e32 v3, v3, v25
	v_mul_f32_e32 v4, v4, v25
	v_mul_f32_e32 v12, v12, v25
	v_cmp_lt_i32_e32 vcc, s9, v24
	s_or_b64 s[6:7], vcc, s[6:7]
	v_mul_f32_e32 v8, v20, v8
	v_mul_f32_e32 v9, v21, v9
	v_add_f32_e32 v20, 1.0, v54
	v_fma_f32 v8, v20, v8, v16
	v_add_f32_e32 v16, 1.0, v55
	v_fma_f32 v9, v16, v9, v17
	v_mul_f32_e32 v10, v22, v10
	v_add_f32_e32 v16, 1.0, v56
	v_fma_f32 v10, v16, v10, v18
	v_mul_f32_e32 v11, v23, v11
	v_add_f32_e32 v16, 1.0, v57
	v_fmac_f32_e32 v19, v16, v11
	v_cvt_pk_bf16_f32 v8, v8, v9
	v_cvt_pk_bf16_f32 v9, v10, v19
	global_store_dwordx2 v[52:53], v[8:9], off
	s_nop 1
	v_mov_b32_e32 v8, v120
	v_mov_b32_e32 v9, v121
	v_mov_b32_e32 v10, v122
	v_mov_b32_e32 v11, v123
	v_mov_b32_e32 v16, v124
	v_mov_b32_e32 v17, v125
	v_mov_b32_e32 v18, v126
	v_mov_b32_e32 v19, v127
	v_mov_b32_e32 v20, v128
	v_mov_b32_e32 v21, v129
	v_mov_b32_e32 v22, v130
	v_mov_b32_e32 v23, v131
	s_nop 0
	v_mul_f32_e32 v0, v8, v0
	v_mul_f32_e32 v1, v9, v1
	v_add_f32_e32 v8, 1.0, v20
	v_fma_f32 v0, v8, v0, v16
	v_add_f32_e32 v8, 1.0, v21
	v_fma_f32 v1, v8, v1, v17
	v_mul_f32_e32 v2, v10, v2
	v_add_f32_e32 v8, 1.0, v22
	v_fma_f32 v2, v8, v2, v18
	v_mul_f32_e32 v3, v11, v3
	v_add_f32_e32 v8, 1.0, v23
	v_fmac_f32_e32 v19, v8, v3
	v_cvt_pk_bf16_f32 v0, v0, v1
	v_cvt_pk_bf16_f32 v1, v2, v19
	global_store_dwordx2 v[52:53], v[0:1], off offset:512
	s_nop 1
	v_mov_b32_e32 v0, v132
	v_mov_b32_e32 v1, v133
	v_mov_b32_e32 v2, v134
	v_mov_b32_e32 v3, v135
	v_mov_b32_e32 v8, v136
	v_mov_b32_e32 v9, v137
	v_mov_b32_e32 v10, v138
	v_mov_b32_e32 v11, v139
	v_mov_b32_e32 v16, v140
	v_mov_b32_e32 v17, v141
	v_mov_b32_e32 v18, v142
	v_mov_b32_e32 v19, v143
	s_nop 0
	v_mul_f32_e32 v0, v4, v0
	v_add_f32_e32 v4, 1.0, v16
	v_fma_f32 v0, v0, v4, v8
	v_mul_f32_e32 v4, v5, v25
	v_mul_f32_e32 v1, v4, v1
	v_add_f32_e32 v4, 1.0, v17
	v_fma_f32 v1, v1, v4, v9
	v_mul_f32_e32 v4, v6, v25
	v_mul_f32_e32 v2, v4, v2
	v_add_f32_e32 v4, 1.0, v18
	v_fma_f32 v2, v2, v4, v10
	v_mul_f32_e32 v4, v7, v25
	v_mul_f32_e32 v3, v4, v3
	v_add_f32_e32 v4, 1.0, v19
	v_fmac_f32_e32 v11, v3, v4
	v_cvt_pk_bf16_f32 v0, v0, v1
	v_cvt_pk_bf16_f32 v1, v2, v11
	global_store_dwordx2 v[52:53], v[0:1], off offset:1024
	s_nop 1
	v_mov_b32_e32 v0, v144
	v_mov_b32_e32 v1, v145
	v_mov_b32_e32 v2, v146
	v_mov_b32_e32 v3, v147
	v_mov_b32_e32 v4, v152
	v_mov_b32_e32 v5, v153
	v_mov_b32_e32 v6, v154
	v_mov_b32_e32 v7, v155
	v_mov_b32_e32 v8, v156
	v_mov_b32_e32 v9, v157
	v_mov_b32_e32 v10, v158
	v_mov_b32_e32 v11, v159
	s_nop 0
	v_mul_f32_e32 v0, v12, v0
	v_add_f32_e32 v8, 1.0, v8
	v_fma_f32 v0, v0, v8, v4
	v_mul_f32_e32 v4, v13, v25
	v_mul_f32_e32 v1, v4, v1
	v_add_f32_e32 v4, 1.0, v9
	v_fma_f32 v1, v1, v4, v5
	v_mul_f32_e32 v4, v14, v25
	v_mul_f32_e32 v2, v4, v2
	v_add_f32_e32 v4, 1.0, v10
	v_fma_f32 v2, v2, v4, v6
	v_mul_f32_e32 v4, v15, v25
	v_mul_f32_e32 v3, v4, v3
	v_add_f32_e32 v4, 1.0, v11
	v_fmac_f32_e32 v7, v3, v4
	v_cvt_pk_bf16_f32 v0, v0, v1
	v_cvt_pk_bf16_f32 v1, v2, v7
	global_store_dwordx2 v[52:53], v[0:1], off offset:1536
	s_andn2_b64 exec, exec, s[6:7]
	s_cbranch_execnz .LBB0_1929

; DEVI void ctx_combine_phase(const Params& p, int l, int gi, float coef, int ln, int lwhich) {
;     ...
;   for (int rc = gw; rc < TC; rc += NW) {
;     f32x4* x4 = (f32x4*)(X + (size_t)(TL + rc) * D) + lane;
;     f32x4 v[4]; float ss = 0.f;
; #pragma unroll
;     for (int j = 0; j < 4; ++j) {
;       f32x4 sum = {0.f, 0.f, 0.f, 0.f};
; #pragma unroll
;       for (int sl = 0; sl < 7; ++sl) {
;         const uint2 w = *((const uint2*)(PS + ((size_t)sl * TC + rc) * D) + lane + 64 * j);
;         sum[0] += __uint_as_float(w.x << 16); sum[1] += __uint_as_float(w.x & 0xffff0000u); sum[2] += __uint_as_float(w.y << 16); sum[3] += __uint_as_float(w.y & 0xffff0000u);
;       }
;       const f32x4 xo = x4[64 * j], gv = gate4[64 * j];
; #pragma unroll
;       for (int q = 0; q < 4; ++q) v[j][q] = xo[q] + coef * gv[q] * sum[q];
;       x4[64 * j] = v[j];
;       ss += (v[j][0] * v[j][0] + v[j][1] * v[j][1]) + (v[j][2] * v[j][2] + v[j][3] * v[j][3]);
.LBB0_2426:
	v_add_co_u32_e32 v12, vcc, 0xfe800000, v50
	v_add_u32_e32 v16, 0x8000, v24
	s_nop 0
	v_addc_co_u32_e32 v13, vcc, -1, v51, vcc
	v_add_co_u32_e32 v14, vcc, 0xfec00000, v50
	v_ashrrev_i32_e32 v17, 31, v16
	s_nop 0
	v_addc_co_u32_e32 v15, vcc, -1, v51, vcc
	v_add_co_u32_e32 v22, vcc, 0xff000000, v50
	v_lshlrev_b64 v[0:1], 12, v[16:17]
	s_nop 0
	v_addc_co_u32_e32 v23, vcc, -1, v51, vcc
	v_add_co_u32_e32 v52, vcc, 0xff400000, v50
	v_lshl_add_u64 v[18:19], v[28:29], 0, v[0:1]
	s_nop 0
	v_addc_co_u32_e32 v53, vcc, -1, v51, vcc
	v_add_co_u32_e32 v54, vcc, 0xff800000, v50
	global_load_dwordx2 v[10:11], v[52:53], off offset:-1540
	s_nop 0
	v_addc_co_u32_e32 v55, vcc, -1, v51, vcc
	global_load_dwordx2 v[56:57], v[54:55], off offset:-1540
	global_load_dwordx2 v[0:1], v[12:13], off offset:-1540
	global_load_dwordx2 v[2:3], v[14:15], off offset:-1540
	global_load_dwordx2 v[6:7], v[22:23], off offset:-1540
	v_add_co_u32_e32 v98, vcc, 0xffc00000, v50
	s_nop 1
	v_addc_co_u32_e32 v99, vcc, -1, v51, vcc
	global_load_dwordx2 v[100:101], v[98:99], off offset:-1540
	global_load_dwordx2 v[102:103], v[50:51], off offset:-1540
	global_load_dwordx4 v[104:107], v[18:19], off
	global_load_dwordx4 v[108:111], v[26:27], off
	global_load_dwordx2 v[112:113], v[12:13], off offset:-1028
	global_load_dwordx2 v[114:115], v[14:15], off offset:-1028
	global_load_dwordx2 v[116:117], v[22:23], off offset:-1028
	global_load_dwordx2 v[118:119], v[52:53], off offset:-1028
	global_load_dwordx2 v[120:121], v[54:55], off offset:-1028
	global_load_dwordx2 v[122:123], v[98:99], off offset:-1028
	global_load_dwordx2 v[124:125], v[50:51], off offset:-1028
	global_load_dwordx4 v[126:129], v[18:19], off offset:1024
	global_load_dwordx4 v[130:133], v[26:27], off offset:1024
	global_load_dwordx2 v[134:135], v[12:13], off offset:-516
	global_load_dwordx2 v[136:137], v[14:15], off offset:-516
	global_load_dwordx2 v[138:139], v[22:23], off offset:-516
	global_load_dwordx2 v[140:141], v[52:53], off offset:-516
	global_load_dwordx2 v[142:143], v[54:55], off offset:-516
	global_load_dwordx2 v[144:145], v[98:99], off offset:-516
	global_load_dwordx2 v[146:147], v[50:51], off offset:-516
	global_load_dwordx4 v[152:155], v[18:19], off offset:2048
	global_load_dwordx4 v[156:159], v[26:27], off offset:2048
	global_load_dwordx2 v[160:161], v[12:13], off offset:-4
	global_load_dwordx2 v[162:163], v[14:15], off offset:-4
	global_load_dwordx2 v[164:165], v[22:23], off offset:-4
	global_load_dwordx2 v[166:167], v[52:53], off offset:-4
	global_load_dwordx2 v[168:169], v[54:55], off offset:-4
	global_load_dwordx2 v[170:171], v[98:99], off offset:-4
	global_load_dwordx2 v[172:173], v[50:51], off offset:-4
	global_load_dwordx4 v[176:179], v[18:19], off offset:3072
	global_load_dwordx4 v[180:183], v[26:27], off offset:3072
	v_lshlrev_b64 v[16:17], 11, v[16:17]
	v_add_u32_e32 v24, s2, v24
	s_waitcnt vmcnt(4)
	v_lshlrev_b32_e32 v60, 16, v10
	v_and_b32_e32 v61, 0xffff0000, v10
	v_lshlrev_b32_e32 v10, 16, v11
	s_waitcnt vmcnt(3)
	v_lshlrev_b32_e32 v70, 16, v56
	v_and_b32_e32 v71, 0xffff0000, v56
	v_add_co_u32_e32 v56, vcc, 0xffc00000, v50
	v_lshlrev_b32_e32 v58, 16, v57
	v_and_b32_e32 v59, 0xffff0000, v57
	v_addc_co_u32_e32 v57, vcc, -1, v51, vcc
	v_and_b32_e32 v11, 0xffff0000, v11
	s_waitcnt vmcnt(0)
	v_mov_b32_e32 v62, v100
	v_mov_b32_e32 v63, v101
	v_lshlrev_b32_e32 v72, 16, v62
	v_and_b32_e32 v73, 0xffff0000, v62
	v_lshlrev_b32_e32 v74, 16, v63
	v_and_b32_e32 v75, 0xffff0000, v63
	v_lshlrev_b32_e32 v4, 16, v0
	v_and_b32_e32 v5, 0xffff0000, v0
	v_lshlrev_b32_e32 v0, 16, v1
	v_and_b32_e32 v1, 0xffff0000, v1
	v_lshlrev_b32_e32 v8, 16, v2
	v_and_b32_e32 v9, 0xffff0000, v2
	v_lshlrev_b32_e32 v2, 16, v3
	v_and_b32_e32 v3, 0xffff0000, v3
	v_pk_add_f32 v[4:5], v[4:5], 0 op_sel_hi:[1,0]
	v_pk_add_f32 v[0:1], v[0:1], 0 op_sel_hi:[1,0]
	v_lshlrev_b32_e32 v20, 16, v6
	v_and_b32_e32 v21, 0xffff0000, v6
	v_lshlrev_b32_e32 v6, 16, v7
	v_and_b32_e32 v7, 0xffff0000, v7
	v_pk_add_f32 v[4:5], v[4:5], v[8:9]
	v_pk_add_f32 v[0:1], v[0:1], v[2:3]
	v_pk_add_f32 v[4:5], v[4:5], v[20:21]
	v_pk_add_f32 v[0:1], v[0:1], v[6:7]
	v_pk_add_f32 v[4:5], v[4:5], v[60:61]
	v_pk_add_f32 v[0:1], v[0:1], v[10:11]
	v_pk_add_f32 v[4:5], v[4:5], v[70:71]
	v_pk_add_f32 v[0:1], v[0:1], v[58:59]
	v_pk_add_f32 v[4:5], v[4:5], v[72:73]
	v_pk_add_f32 v[0:1], v[0:1], v[74:75]
	s_waitcnt vmcnt(0)
	v_mov_b32_e32 v62, v102
	v_mov_b32_e32 v63, v103
	v_lshlrev_b32_e32 v76, 16, v62
	v_and_b32_e32 v77, 0xffff0000, v62
	v_lshlrev_b32_e32 v78, 16, v63
	v_and_b32_e32 v79, 0xffff0000, v63
	v_pk_add_f32 v[4:5], v[4:5], v[76:77]
	v_pk_add_f32 v[0:1], v[0:1], v[78:79]
	s_waitcnt vmcnt(0)
	v_mov_b32_e32 v66, v108
	v_mov_b32_e32 v67, v109
	v_mov_b32_e32 v68, v110
	v_mov_b32_e32 v69, v111
	v_mov_b32_e32 v62, v104
	v_mov_b32_e32 v63, v105
	v_mov_b32_e32 v64, v106
	v_mov_b32_e32 v65, v107
	v_pk_mul_f32 v[8:9], v[66:67], 0.5 op_sel_hi:[1,0]
	v_pk_mul_f32 v[2:3], v[68:69], 0.5 op_sel_hi:[1,0]
	v_pk_fma_f32 v[8:9], v[4:5], v[8:9], v[62:63]
	v_pk_fma_f32 v[10:11], v[0:1], v[2:3], v[64:65]
	v_mov_b32_e32 v2, v9
	v_mov_b32_e32 v3, v11
	v_mov_b32_e32 v0, v8
	v_mov_b32_e32 v1, v10
	v_pk_mul_f32 v[2:3], v[2:3], v[2:3]
	global_store_dwordx4 v[18:19], v[8:11], off
	v_pk_fma_f32 v[0:1], v[0:1], v[0:1], v[2:3]
	s_nop 0
	v_pk_add_f32 v[20:21], v[0:1], v[0:1] op_sel:[0,1] op_sel_hi:[1,0]
	s_waitcnt vmcnt(0)
	v_mov_b32_e32 v0, v112
	v_mov_b32_e32 v1, v113
	v_lshlrev_b32_e32 v58, 16, v0
	v_and_b32_e32 v59, 0xffff0000, v0
	v_lshlrev_b32_e32 v4, 16, v1
	v_and_b32_e32 v5, 0xffff0000, v1
	v_pk_add_f32 v[58:59], v[58:59], 0 op_sel_hi:[1,0]
	v_pk_add_f32 v[4:5], v[4:5], 0 op_sel_hi:[1,0]
	s_waitcnt vmcnt(0)
; DEVI void ctx_combine_phase(const Params& p, int l, int gi, float coef, int ln, int lwhich) {
;     ...
;     for (int j = 0; j < 4; ++j) {
;       f32x4 sum = {0.f, 0.f, 0.f, 0.f};
; #pragma unroll
;       for (int sl = 0; sl < 7; ++sl) {
;         const uint2 w = *((const uint2*)(PS + ((size_t)sl * TC + rc) * D) + lane + 64 * j);
;         sum[0] += __uint_as_float(w.x << 16); sum[1] += __uint_as_float(w.x & 0xffff0000u); sum[2] += __uint_as_float(w.y << 16); sum[3] += __uint_as_float(w.y & 0xffff0000u);
;       }
;       const f32x4 xo = x4[64 * j], gv = gate4[64 * j];
; #pragma unroll
;       for (int q = 0; q < 4; ++q) v[j][q] = xo[q] + coef * gv[q] * sum[q];
;       x4[64 * j] = v[j];
;       ss += (v[j][0] * v[j][0] + v[j][1] * v[j][1]) + (v[j][2] * v[j][2] + v[j][3] * v[j][3]);
	v_mov_b32_e32 v0, v114
	v_mov_b32_e32 v1, v115
	v_lshlrev_b32_e32 v62, 16, v0
	v_and_b32_e32 v63, 0xffff0000, v0
	v_lshlrev_b32_e32 v6, 16, v1
	v_and_b32_e32 v7, 0xffff0000, v1
	v_pk_add_f32 v[58:59], v[58:59], v[62:63]
	v_pk_add_f32 v[4:5], v[4:5], v[6:7]
	s_waitcnt vmcnt(0)
	v_mov_b32_e32 v0, v116
	v_mov_b32_e32 v1, v117
	v_lshlrev_b32_e32 v66, 16, v0
	v_and_b32_e32 v67, 0xffff0000, v0
	v_lshlrev_b32_e32 v60, 16, v1
	v_and_b32_e32 v61, 0xffff0000, v1
	v_pk_add_f32 v[58:59], v[58:59], v[66:67]
	v_pk_add_f32 v[4:5], v[4:5], v[60:61]
	s_waitcnt vmcnt(0)
	v_mov_b32_e32 v0, v118
	v_mov_b32_e32 v1, v119
	v_lshlrev_b32_e32 v70, 16, v0
	v_and_b32_e32 v71, 0xffff0000, v0
	v_lshlrev_b32_e32 v64, 16, v1
	v_and_b32_e32 v65, 0xffff0000, v1
	v_pk_add_f32 v[58:59], v[58:59], v[70:71]
	v_pk_add_f32 v[4:5], v[4:5], v[64:65]
	s_waitcnt vmcnt(0)
	v_mov_b32_e32 v0, v120
	v_mov_b32_e32 v1, v121
	v_lshlrev_b32_e32 v74, 16, v0
	v_and_b32_e32 v75, 0xffff0000, v0
	v_lshlrev_b32_e32 v68, 16, v1
	v_and_b32_e32 v69, 0xffff0000, v1
	v_pk_add_f32 v[58:59], v[58:59], v[74:75]
	v_pk_add_f32 v[4:5], v[4:5], v[68:69]
	s_waitcnt vmcnt(0)
	v_mov_b32_e32 v0, v122
	v_mov_b32_e32 v1, v123
	v_lshlrev_b32_e32 v78, 16, v0
	v_and_b32_e32 v79, 0xffff0000, v0
	v_lshlrev_b32_e32 v72, 16, v1
	v_and_b32_e32 v73, 0xffff0000, v1
	v_pk_add_f32 v[58:59], v[58:59], v[78:79]
	v_pk_add_f32 v[4:5], v[4:5], v[72:73]
	s_waitcnt vmcnt(0)
	v_mov_b32_e32 v0, v124
	v_mov_b32_e32 v1, v125
	v_lshlrev_b32_e32 v80, 16, v0
	v_and_b32_e32 v81, 0xffff0000, v0
	v_lshlrev_b32_e32 v76, 16, v1
	v_and_b32_e32 v77, 0xffff0000, v1
	v_pk_add_f32 v[58:59], v[58:59], v[80:81]
	v_pk_add_f32 v[4:5], v[4:5], v[76:77]
	s_waitcnt vmcnt(0)
	v_mov_b32_e32 v82, v130
	v_mov_b32_e32 v83, v131
	v_mov_b32_e32 v84, v132
	v_mov_b32_e32 v85, v133
	v_mov_b32_e32 v0, v126
	v_mov_b32_e32 v1, v127
	v_mov_b32_e32 v2, v128
	v_mov_b32_e32 v3, v129
	v_pk_mul_f32 v[62:63], v[82:83], 0.5 op_sel_hi:[1,0]
	v_pk_mul_f32 v[6:7], v[84:85], 0.5 op_sel_hi:[1,0]
	v_pk_fma_f32 v[0:1], v[58:59], v[62:63], v[0:1]
	v_pk_fma_f32 v[2:3], v[4:5], v[6:7], v[2:3]
	v_mov_b32_e32 v6, v1
	v_mov_b32_e32 v7, v3
	v_mov_b32_e32 v4, v0
	v_mov_b32_e32 v5, v2
	v_pk_mul_f32 v[6:7], v[6:7], v[6:7]
	global_store_dwordx4 v[18:19], v[0:3], off offset:1024
	v_pk_fma_f32 v[4:5], v[4:5], v[4:5], v[6:7]
	s_nop 0
	v_pk_add_f32 v[58:59], v[4:5], v[4:5] op_sel:[0,1] op_sel_hi:[1,0]
	s_waitcnt vmcnt(0)
	v_mov_b32_e32 v4, v134
	v_mov_b32_e32 v5, v135
	v_lshlrev_b32_e32 v64, 16, v4
	v_and_b32_e32 v65, 0xffff0000, v4
	v_lshlrev_b32_e32 v60, 16, v5
	v_and_b32_e32 v61, 0xffff0000, v5
	v_pk_add_f32 v[64:65], v[64:65], 0 op_sel_hi:[1,0]
	v_pk_add_f32 v[60:61], v[60:61], 0 op_sel_hi:[1,0]
	s_waitcnt vmcnt(0)
	v_mov_b32_e32 v4, v136
	v_mov_b32_e32 v5, v137
	v_lshlrev_b32_e32 v68, 16, v4
	v_and_b32_e32 v69, 0xffff0000, v4
	v_lshlrev_b32_e32 v62, 16, v5
	v_and_b32_e32 v63, 0xffff0000, v5
	v_pk_add_f32 v[64:65], v[64:65], v[68:69]
	v_pk_add_f32 v[60:61], v[60:61], v[62:63]
	s_waitcnt vmcnt(0)
	v_mov_b32_e32 v4, v138
	v_mov_b32_e32 v5, v139
	v_lshlrev_b32_e32 v72, 16, v4
	v_and_b32_e32 v73, 0xffff0000, v4
	v_lshlrev_b32_e32 v66, 16, v5
	v_and_b32_e32 v67, 0xffff0000, v5
	v_pk_add_f32 v[64:65], v[64:65], v[72:73]
	v_pk_add_f32 v[60:61], v[60:61], v[66:67]
	s_waitcnt vmcnt(0)
	v_mov_b32_e32 v4, v140
	v_mov_b32_e32 v5, v141
	v_lshlrev_b32_e32 v76, 16, v4
	v_and_b32_e32 v77, 0xffff0000, v4
	v_lshlrev_b32_e32 v70, 16, v5
	v_and_b32_e32 v71, 0xffff0000, v5
	v_pk_add_f32 v[64:65], v[64:65], v[76:77]
	v_pk_add_f32 v[60:61], v[60:61], v[70:71]
	s_waitcnt vmcnt(0)
	v_mov_b32_e32 v4, v142
	v_mov_b32_e32 v5, v143
	v_lshlrev_b32_e32 v80, 16, v4
	v_and_b32_e32 v81, 0xffff0000, v4
	v_lshlrev_b32_e32 v74, 16, v5
	v_and_b32_e32 v75, 0xffff0000, v5
	v_pk_add_f32 v[64:65], v[64:65], v[80:81]
	v_pk_add_f32 v[60:61], v[60:61], v[74:75]
	s_waitcnt vmcnt(0)
	v_mov_b32_e32 v4, v144
	v_mov_b32_e32 v5, v145
	v_lshlrev_b32_e32 v84, 16, v4
	v_and_b32_e32 v85, 0xffff0000, v4
	v_lshlrev_b32_e32 v78, 16, v5
	v_and_b32_e32 v79, 0xffff0000, v5
	v_pk_add_f32 v[64:65], v[64:65], v[84:85]
	v_pk_add_f32 v[60:61], v[60:61], v[78:79]
	s_waitcnt vmcnt(0)
	v_mov_b32_e32 v4, v146
	v_mov_b32_e32 v5, v147
	v_lshlrev_b32_e32 v86, 16, v4
	v_and_b32_e32 v87, 0xffff0000, v4
	v_lshlrev_b32_e32 v82, 16, v5
	v_and_b32_e32 v83, 0xffff0000, v5
	v_pk_add_f32 v[64:65], v[64:65], v[86:87]
	v_pk_add_f32 v[60:61], v[60:61], v[82:83]
	s_waitcnt vmcnt(0)
	v_mov_b32_e32 v94, v156
	v_mov_b32_e32 v95, v157
	v_mov_b32_e32 v96, v158
	v_mov_b32_e32 v97, v159
	v_mov_b32_e32 v4, v152
	v_mov_b32_e32 v5, v153
	v_mov_b32_e32 v6, v154
	v_mov_b32_e32 v7, v155
	v_pk_mul_f32 v[68:69], v[94:95], 0.5 op_sel_hi:[1,0]
	v_pk_mul_f32 v[62:63], v[96:97], 0.5 op_sel_hi:[1,0]
	v_pk_fma_f32 v[4:5], v[64:65], v[68:69], v[4:5]
	v_pk_fma_f32 v[6:7], v[60:61], v[62:63], v[6:7]
	global_store_dwordx4 v[18:19], v[4:7], off offset:2048
	v_mul_f32_e32 v60, v5, v5
	v_mul_f32_e32 v62, v7, v7
	v_pk_fma_f32 v[60:61], v[4:5], v[4:5], v[60:61] op_sel_hi:[1,1,0]
	v_pk_fma_f32 v[62:63], v[6:7], v[6:7], v[62:63] op_sel_hi:[1,1,0]
	s_waitcnt vmcnt(0)
	v_mov_b32_e32 v12, v160
	v_mov_b32_e32 v13, v161
	v_lshlrev_b32_e32 v68, 16, v12
	v_and_b32_e32 v69, 0xffff0000, v12
	v_lshlrev_b32_e32 v64, 16, v13
	v_and_b32_e32 v65, 0xffff0000, v13
	v_pk_add_f32 v[68:69], v[68:69], 0 op_sel_hi:[1,0]
	v_pk_add_f32 v[64:65], v[64:65], 0 op_sel_hi:[1,0]
	s_waitcnt vmcnt(0)
	v_mov_b32_e32 v12, v162
	v_mov_b32_e32 v13, v163
	v_lshlrev_b32_e32 v70, 16, v12
	v_and_b32_e32 v71, 0xffff0000, v12
	v_lshlrev_b32_e32 v66, 16, v13
	v_and_b32_e32 v67, 0xffff0000, v13
	v_pk_add_f32 v[68:69], v[68:69], v[70:71]
	v_pk_add_f32 v[64:65], v[64:65], v[66:67]
	s_waitcnt vmcnt(0)
; DEVI void ctx_combine_phase(const Params& p, int l, int gi, float coef, int ln, int lwhich) {
;     ...
;       for (int sl = 0; sl < 7; ++sl) {
;         const uint2 w = *((const uint2*)(PS + ((size_t)sl * TC + rc) * D) + lane + 64 * j);
;         sum[0] += __uint_as_float(w.x << 16); sum[1] += __uint_as_float(w.x & 0xffff0000u); sum[2] += __uint_as_float(w.y << 16); sum[3] += __uint_as_float(w.y & 0xffff0000u);
;       }
;       const f32x4 xo = x4[64 * j], gv = gate4[64 * j];
; #pragma unroll
;       for (int q = 0; q < 4; ++q) v[j][q] = xo[q] + coef * gv[q] * sum[q];
;       x4[64 * j] = v[j];
;       ss += (v[j][0] * v[j][0] + v[j][1] * v[j][1]) + (v[j][2] * v[j][2] + v[j][3] * v[j][3]);
;     }
;     if (ln >= 0) {
;       const f32x4* g4 = (const f32x4*)(p.in[6] + (size_t)(ln * 3 + lwhich) * D) + lane;
;       const f32x4* sh4 = (const f32x4*)(MOD + (size_t)((ln * 9 + 8) * 9 + lwhich * 3) * D) + lane;
;       const f32x4* sc4 = sh4 + D / 4;
;       const float rinv = rsqrtf(wave_sum(ss, lane) * (1.f / D) + 1e-6f);
;       uint2* o8 = (uint2*)(H + (size_t)(TL + rc) * D) + lane;
; #pragma unroll
;       for (int j = 0; j < 4; ++j) {
;         const f32x4 g = g4[64 * j], sh = sh4[64 * j], sc = sc4[64 * j];
	v_mov_b32_e32 v12, v164
	v_mov_b32_e32 v13, v165
	v_lshlrev_b32_e32 v72, 16, v12
	v_and_b32_e32 v73, 0xffff0000, v12
	v_lshlrev_b32_e32 v22, 16, v13
	v_and_b32_e32 v23, 0xffff0000, v13
	v_pk_add_f32 v[68:69], v[68:69], v[72:73]
	v_pk_add_f32 v[22:23], v[64:65], v[22:23]
	s_waitcnt vmcnt(0)
	v_mov_b32_e32 v12, v166
	v_mov_b32_e32 v13, v167
	v_lshlrev_b32_e32 v74, 16, v12
	v_and_b32_e32 v75, 0xffff0000, v12
	v_lshlrev_b32_e32 v52, 16, v13
	v_and_b32_e32 v53, 0xffff0000, v13
	v_pk_add_f32 v[68:69], v[68:69], v[74:75]
	v_pk_add_f32 v[22:23], v[22:23], v[52:53]
	s_waitcnt vmcnt(0)
	v_mov_b32_e32 v12, v168
	v_mov_b32_e32 v13, v169
	v_lshlrev_b32_e32 v76, 16, v12
	v_and_b32_e32 v77, 0xffff0000, v12
	v_lshlrev_b32_e32 v54, 16, v13
	v_and_b32_e32 v55, 0xffff0000, v13
	v_pk_add_f32 v[68:69], v[68:69], v[76:77]
	v_pk_add_f32 v[22:23], v[22:23], v[54:55]
	s_waitcnt vmcnt(0)
	v_mov_b32_e32 v12, v170
	v_mov_b32_e32 v13, v171
	v_lshlrev_b32_e32 v80, 16, v12
	v_and_b32_e32 v81, 0xffff0000, v12
	v_lshlrev_b32_e32 v56, 16, v13
	v_and_b32_e32 v57, 0xffff0000, v13
	v_pk_add_f32 v[68:69], v[68:69], v[80:81]
	v_pk_add_f32 v[22:23], v[22:23], v[56:57]
	v_lshl_add_u64 v[50:51], v[50:51], 0, s[10:11]
	s_waitcnt vmcnt(0)
	v_mov_b32_e32 v12, v172
	v_mov_b32_e32 v13, v173
	v_lshlrev_b32_e32 v82, 16, v12
	v_and_b32_e32 v83, 0xffff0000, v12
	v_lshlrev_b32_e32 v78, 16, v13
	v_and_b32_e32 v79, 0xffff0000, v13
	v_pk_add_f32 v[68:69], v[68:69], v[82:83]
	v_pk_add_f32 v[22:23], v[22:23], v[78:79]
	s_waitcnt vmcnt(0)
	global_load_dwordx4 v[100:103], v[48:49], off
	global_load_dwordx4 v[112:115], v[32:33], off
	global_load_dwordx4 v[116:119], v[34:35], off
	global_load_dwordx4 v[120:123], v[48:49], off offset:1024
	global_load_dwordx4 v[124:127], v[36:37], off
	global_load_dwordx4 v[128:131], v[38:39], off
	global_load_dwordx4 v[132:135], v[48:49], off offset:2048
	global_load_dwordx4 v[136:139], v[40:41], off
	global_load_dwordx4 v[140:143], v[42:43], off
	global_load_dwordx4 v[144:147], v[48:49], off offset:3072
	global_load_dwordx4 v[152:155], v[44:45], off
	global_load_dwordx4 v[156:159], v[46:47], off
	v_mov_b32_e32 v84, v180
	v_mov_b32_e32 v85, v181
	v_mov_b32_e32 v86, v182
	v_mov_b32_e32 v87, v183
	v_mov_b32_e32 v12, v176
	v_mov_b32_e32 v13, v177
	v_mov_b32_e32 v14, v178
	v_mov_b32_e32 v15, v179
	v_pk_mul_f32 v[70:71], v[84:85], 0.5 op_sel_hi:[1,0]
	v_pk_mul_f32 v[52:53], v[86:87], 0.5 op_sel_hi:[1,0]
	v_pk_fma_f32 v[12:13], v[68:69], v[70:71], v[12:13]
	v_pk_fma_f32 v[14:15], v[22:23], v[52:53], v[14:15]
	global_store_dwordx4 v[18:19], v[12:15], off offset:3072
	v_pk_mul_f32 v[18:19], v[12:13], v[12:13]
	v_pk_mul_f32 v[22:23], v[14:15], v[14:15]
	v_mov_b32_e32 v21, v18
	v_mov_b32_e32 v59, v19
	v_mov_b32_e32 v61, v22
	v_mov_b32_e32 v63, v23
	v_pk_add_f32 v[18:19], v[20:21], v[58:59]
	v_pk_add_f32 v[20:21], v[60:61], v[62:63]
	v_lshl_add_u64 v[52:53], v[30:31], 0, v[16:17]
	v_pk_add_f32 v[18:19], v[18:19], v[20:21]
	s_nop 0
	v_add_f32_e32 v18, v18, v19
	ds_bpermute_b32 v19, v88, v18
	s_waitcnt lgkmcnt(0)
	v_add_f32_e32 v18, v18, v19
	ds_bpermute_b32 v19, v89, v18
	s_waitcnt lgkmcnt(0)
	v_add_f32_e32 v18, v18, v19
	ds_bpermute_b32 v19, v90, v18
	s_waitcnt lgkmcnt(0)
	v_add_f32_e32 v18, v18, v19
	ds_bpermute_b32 v19, v91, v18
	s_waitcnt lgkmcnt(0)
	v_add_f32_e32 v18, v18, v19
	ds_bpermute_b32 v19, v92, v18
	s_waitcnt lgkmcnt(0)
	v_add_f32_e32 v18, v18, v19
	ds_bpermute_b32 v19, v93, v18
	s_waitcnt lgkmcnt(0)
	v_add_f32_e32 v18, v18, v19
	v_fmamk_f32 v18, v18, 0x3a800000, v230
	v_cmp_gt_f32_e32 vcc, s8, v18
	v_mul_f32_e32 v19, 0x4b800000, v18
	s_nop 0
	v_cndmask_b32_e32 v18, v18, v19, vcc
	v_rsq_f32_e32 v18, v18
	s_nop 0
	v_mul_f32_e32 v19, 0x45800000, v18
	v_cndmask_b32_e32 v25, v18, v19, vcc
	s_waitcnt vmcnt(0)
; DEVI unsigned pk_bf16(float lo, float hi) { unsigned r; asm volatile("v_cvt_pk_bf16_f32 %0, %1, %2" : "=v"(r) : "v"(lo), "v"(hi)); return r; }
; DEVI void ctx_combine_phase(const Params& p, int l, int gi, float coef, int ln, int lwhich) {
;     ...
; #pragma unroll
;       for (int j = 0; j < 4; ++j) {
;         const f32x4 g = g4[64 * j], sh = sh4[64 * j], sc = sc4[64 * j];
;         f32x4 y;
; #pragma unroll
;         for (int q = 0; q < 4; ++q) y[q] = v[j][q] * rinv * g[q] * (1.f + sc[q]) + sh[q];
;         uint2 o; o.x = pk_bf16(y[0], y[1]); o.y = pk_bf16(y[2], y[3]); o8[64 * j] = o;
;       }
	v_mov_b32_e32 v20, v100
	v_mov_b32_e32 v21, v101
	v_mov_b32_e32 v22, v102
	v_mov_b32_e32 v23, v103
	v_mov_b32_e32 v16, v112
	v_mov_b32_e32 v17, v113
	v_mov_b32_e32 v18, v114
	v_mov_b32_e32 v19, v115
	v_mov_b32_e32 v54, v116
	v_mov_b32_e32 v55, v117
	v_mov_b32_e32 v56, v118
	v_mov_b32_e32 v57, v119
	v_mul_f32_e32 v8, v8, v25
	v_mul_f32_e32 v9, v9, v25
	v_mul_f32_e32 v10, v10, v25
	v_mul_f32_e32 v11, v11, v25
	v_mul_f32_e32 v0, v0, v25
	v_mul_f32_e32 v1, v1, v25
	v_mul_f32_e32 v2, v2, v25
	v_mul_f32_e32 v3, v3, v25
	v_mul_f32_e32 v4, v4, v25
	v_mul_f32_e32 v12, v12, v25
	v_cmp_lt_i32_e32 vcc, s24, v24
	s_or_b64 s[6:7], vcc, s[6:7]
	v_mul_f32_e32 v8, v20, v8
	v_mul_f32_e32 v9, v21, v9
	v_add_f32_e32 v20, 1.0, v54
	v_fma_f32 v8, v20, v8, v16
	v_add_f32_e32 v16, 1.0, v55
	v_fma_f32 v9, v16, v9, v17
	v_mul_f32_e32 v10, v22, v10
	v_add_f32_e32 v16, 1.0, v56
	v_fma_f32 v10, v16, v10, v18
	v_mul_f32_e32 v11, v23, v11
	v_add_f32_e32 v16, 1.0, v57
	v_fmac_f32_e32 v19, v16, v11
	v_cvt_pk_bf16_f32 v8, v8, v9
	v_cvt_pk_bf16_f32 v9, v10, v19
	global_store_dwordx2 v[52:53], v[8:9], off
	s_nop 1
	v_mov_b32_e32 v8, v120
	v_mov_b32_e32 v9, v121
	v_mov_b32_e32 v10, v122
	v_mov_b32_e32 v11, v123
	v_mov_b32_e32 v16, v124
	v_mov_b32_e32 v17, v125
	v_mov_b32_e32 v18, v126
	v_mov_b32_e32 v19, v127
	v_mov_b32_e32 v20, v128
	v_mov_b32_e32 v21, v129
	v_mov_b32_e32 v22, v130
	v_mov_b32_e32 v23, v131
	s_nop 0
	v_mul_f32_e32 v0, v8, v0
	v_mul_f32_e32 v1, v9, v1
	v_add_f32_e32 v8, 1.0, v20
	v_fma_f32 v0, v8, v0, v16
	v_add_f32_e32 v8, 1.0, v21
	v_fma_f32 v1, v8, v1, v17
	v_mul_f32_e32 v2, v10, v2
	v_add_f32_e32 v8, 1.0, v22
	v_fma_f32 v2, v8, v2, v18
	v_mul_f32_e32 v3, v11, v3
	v_add_f32_e32 v8, 1.0, v23
	v_fmac_f32_e32 v19, v8, v3
	v_cvt_pk_bf16_f32 v0, v0, v1
	v_cvt_pk_bf16_f32 v1, v2, v19
	global_store_dwordx2 v[52:53], v[0:1], off offset:512
	s_nop 1
	v_mov_b32_e32 v0, v132
	v_mov_b32_e32 v1, v133
	v_mov_b32_e32 v2, v134
	v_mov_b32_e32 v3, v135
	v_mov_b32_e32 v8, v136
	v_mov_b32_e32 v9, v137
	v_mov_b32_e32 v10, v138
	v_mov_b32_e32 v11, v139
	v_mov_b32_e32 v16, v140
	v_mov_b32_e32 v17, v141
	v_mov_b32_e32 v18, v142
	v_mov_b32_e32 v19, v143
	s_nop 0
	v_mul_f32_e32 v0, v4, v0
	v_add_f32_e32 v4, 1.0, v16
	v_fma_f32 v0, v0, v4, v8
	v_mul_f32_e32 v4, v5, v25
	v_mul_f32_e32 v1, v4, v1
	v_add_f32_e32 v4, 1.0, v17
	v_fma_f32 v1, v1, v4, v9
	v_mul_f32_e32 v4, v6, v25
	v_mul_f32_e32 v2, v4, v2
	v_add_f32_e32 v4, 1.0, v18
	v_fma_f32 v2, v2, v4, v10
	v_mul_f32_e32 v4, v7, v25
	v_mul_f32_e32 v3, v4, v3
	v_add_f32_e32 v4, 1.0, v19
	v_fmac_f32_e32 v11, v3, v4
	v_cvt_pk_bf16_f32 v0, v0, v1
	v_cvt_pk_bf16_f32 v1, v2, v11
	global_store_dwordx2 v[52:53], v[0:1], off offset:1024
	s_nop 1
	v_mov_b32_e32 v0, v144
	v_mov_b32_e32 v1, v145
	v_mov_b32_e32 v2, v146
	v_mov_b32_e32 v3, v147
	v_mov_b32_e32 v4, v152
	v_mov_b32_e32 v5, v153
	v_mov_b32_e32 v6, v154
	v_mov_b32_e32 v7, v155
	v_mov_b32_e32 v8, v156
	v_mov_b32_e32 v9, v157
	v_mov_b32_e32 v10, v158
	v_mov_b32_e32 v11, v159
	s_nop 0
	v_mul_f32_e32 v0, v12, v0
	v_add_f32_e32 v8, 1.0, v8
	v_fma_f32 v0, v0, v8, v4
	v_mul_f32_e32 v4, v13, v25
	v_mul_f32_e32 v1, v4, v1
	v_add_f32_e32 v4, 1.0, v9
	v_fma_f32 v1, v1, v4, v5
	v_mul_f32_e32 v4, v14, v25
	v_mul_f32_e32 v2, v4, v2
	v_add_f32_e32 v4, 1.0, v10
	v_fma_f32 v2, v2, v4, v6
	v_mul_f32_e32 v4, v15, v25
	v_mul_f32_e32 v3, v4, v3
	v_add_f32_e32 v4, 1.0, v11
	v_fmac_f32_e32 v7, v3, v4
	v_cvt_pk_bf16_f32 v0, v0, v1
	v_cvt_pk_bf16_f32 v1, v2, v7
	global_store_dwordx2 v[52:53], v[0:1], off offset:1536
	s_andn2_b64 exec, exec, s[6:7]
	s_cbranch_execnz .LBB0_2426
